# softmax row max across wave halves via v_permlane32_swap (VALU) instead of ds_bpermute (LDS round trip) in DA/NSA steps
# baseline (speedup 1.0000x reference)
; #define LAS __attribute__((address_space(3)))
; template <bool LOAD2, bool MASK>
; DI void da_step(lds8* lds, const DaCtx& cx, int t, const bf16x8 (&q)[4], f32x16 (&O)[4], float& muse, float& l, f32x16& negm) {
;   u32x4 kr0, kr1, vr0, vr1;
;   if (LOAD2) { const size_t ro = (size_t)(t + 2) * 64;
;     kr0 = *(const u32x4*)(cx.kg + (ro + cx.sr0) * DM + cx.sc0 * 8); kr1 = *(const u32x4*)(cx.kg + (ro + cx.sr1) * DM + cx.sc1 * 8);
; DI void da_unit(const Params& p, lds8* lds, int bl, int hd, int qb, float lam) {
;   int tid = threadIdx.x; asm volatile("" : "+v"(tid));
;   const int lane = tid & 63, wid = __builtin_amdgcn_readfirstlane(tid >> 6);
;   unsigned char* ws = p.ws;
;   bf16_t* QDA = (bf16_t*)(ws + OFF_QDA); const bf16_t* KDA = (const bf16_t*)(ws + OFF_KDA); const bf16_t* VDA = (const bf16_t*)(ws + OFF_VDA);
;   const int r = lane & 31, h = lane >> 5, qs = wid & 3, c = wid >> 2;
;   const size_t rowbase = (size_t)bl * SEQ; const int q0 = qb * 128; const int qpos = q0 + 32 * qs + r;
;   bf16x8 q[4];
;   { const bf16_t* qp = QDA + (rowbase + qpos) * DM + hd * 128 + c * 64 + 8 * h;
; #pragma unroll
;     for (int ks = 0; ks < 4; ++ks) q[ks] = *(const bf16x8*)(qp + 16 * ks); }
;   const int nt = 2 * (qb + 1);
;   DaCtx cx;
;   { const int ch0 = tid, ch1 = tid + 512; cx.sr0 = ch0 >> 4; cx.sc0 = ch0 & 15; cx.sr1 = ch1 >> 4; cx.sc1 = ch1 & 15; }
;   cx.kg = KDA + rowbase * DM + hd * 128; cx.vg = VDA + rowbase * DM + hd * 128;
;   cx.koff = r * DA_KSTR + h * 16 + c * 128;
;   cx.voff = 64 * DA_KSTR + (4 * h + ((lane & 15) >> 2)) * DA_KSTR + ((lane >> 4) & 1) * 32 + (lane & 3) * 8;
;   cx.qpos = qpos; cx.h = h; cx.qs = qs; cx.q0 = q0;
; #pragma unroll
;   for (int t0 = 0; t0 < 2; ++t0) { const size_t ro = (size_t)t0 * 64; lds8* b = lds + t0 * DA_STAGE;
;     const u32x4 kr0 = *(const u32x4*)(cx.kg + (ro + cx.sr0) * DM + cx.sc0 * 8), kr1 = *(const u32x4*)(cx.kg + (ro + cx.sr1) * DM + cx.sc1 * 8);
;     const u32x4 vr0 = *(const u32x4*)(cx.vg + (ro + cx.sr0) * DM + cx.sc0 * 8), vr1 = *(const u32x4*)(cx.vg + (ro + cx.sr1) * DM + cx.sc1 * 8);
;     *(LAS u32x4*)(b + cx.sr0 * DA_KSTR + cx.sc0 * 16) = kr0; *(LAS u32x4*)(b + cx.sr1 * DA_KSTR + cx.sc1 * 16) = kr1;
;     *(LAS u32x4*)(b + 64 * DA_KSTR + cx.sr0 * DA_KSTR + cx.sc0 * 16) = vr0; *(LAS u32x4*)(b + 64 * DA_KSTR + cx.sr1 * DA_KSTR + cx.sc1 * 16) = vr1; }
;   __syncthreads();
.LBB0_845:
	s_or_b64 exec, exec, s[10:11]
	v_mov_b32_e32 v134, v200
	s_ashr_i32 s6, s20, 7
	s_sub_i32 s12, 15, s6
	v_readfirstlane_b32 s16, v134
	s_bfe_u32 s14, s16, 0x20006
	s_lshl_b32 s1, s12, 7
	s_lshl_b32 s3, s14, 5
	s_bfe_u32 s13, s20, 0x40003
	v_and_b32_e32 v179, 31, v134
	s_or_b32 s18, s3, s1
	s_lshl_b32 s0, s13, 11
	v_or_b32_e32 v183, s18, v179
	v_add_u32_e32 v186, s0, v183
	v_readlane_b32 s10, v254, 43
	v_lshlrev_b64 v[0:1], 11, v[186:187]
	v_readlane_b32 s11, v254, 44
	s_ashr_i32 s17, s16, 8
	v_bfe_u32 v135, v134, 5, 1
	v_lshl_add_u64 v[0:1], s[10:11], 0, v[0:1]
	s_lshl_b32 s10, s20, 7
	s_and_b32 s15, s10, 0x380
	s_lshl_b32 s88, s15, 1
	s_lshl_b32 s10, s17, 6
	v_lshl_add_u64 v[0:1], v[0:1], 0, s[88:89]
	s_ashr_i32 s11, s10, 31
	v_lshl_add_u64 v[2:3], s[10:11], 1, v[0:1]
	s_lshl_b32 s10, s13, 22
	v_readlane_b32 s2, v254, 45
	v_lshlrev_b32_e32 v0, 4, v135
	v_mov_b32_e32 v1, v187
	s_add_u32 s11, s2, s10
	v_readlane_b32 s2, v254, 46
	v_lshl_add_u64 v[2:3], v[2:3], 0, v[0:1]
	s_addc_u32 s13, s2, 0
	global_load_dwordx4 v[172:175], v[2:3], off
	global_load_dwordx4 v[168:171], v[2:3], off offset:32
	global_load_dwordx4 v[164:167], v[2:3], off offset:64
	global_load_dwordx4 v[160:163], v[2:3], off offset:96
	s_add_u32 s22, s11, s88
	v_lshlrev_b32_e32 v3, 1, v134
	v_ashrrev_i32_e32 v2, 4, v134
	v_and_b32_e32 v136, 15, v134
	s_addc_u32 s23, s13, 0
	v_readlane_b32 s2, v254, 47
	v_and_b32_e32 v100, 32, v3
	v_lshlrev_b32_e32 v3, 3, v134
	v_add_u32_e32 v1, 0x200, v134
	s_add_u32 s10, s2, s10
	v_readlane_b32 s2, v254, 48
	v_and_b32_e32 v101, 24, v3
	v_ashrrev_i32_e32 v3, 31, v2
	v_lshlrev_b32_e32 v186, 4, v136
	v_ashrrev_i32_e32 v4, 4, v1
	s_addc_u32 s11, s2, 0
	v_lshl_add_u64 v[6:7], s[22:23], 0, v[186:187]
	v_lshlrev_b64 v[96:97], 11, v[2:3]
	s_add_u32 s24, s10, s88
	v_ashrrev_i32_e32 v5, 31, v4
	v_lshl_add_u64 v[8:9], v[6:7], 0, v[96:97]
	s_addc_u32 s25, s11, 0
	global_load_dwordx4 v[10:13], v[8:9], off
	v_lshlrev_b64 v[98:99], 11, v[4:5]
	v_lshl_add_u64 v[22:23], s[24:25], 0, v[186:187]
	s_movk_i32 s2, 0x130
	v_lshl_add_u64 v[6:7], v[6:7], 0, v[98:99]
	v_mul_lo_u32 v138, v4, s2
	global_load_dwordx4 v[14:17], v[6:7], off
	v_lshl_add_u64 v[4:5], v[22:23], 0, v[96:97]
	v_mul_lo_u32 v137, v2, s2
	global_load_dwordx4 v[18:21], v[4:5], off
	v_lshl_add_u64 v[2:3], v[22:23], 0, v[98:99]
	global_load_dwordx4 v[22:25], v[2:3], off
	v_add3_u32 v26, 0, v137, v186
	s_mov_b32 s2, 0x20000
	v_add3_u32 v27, 0, v138, v186
	v_lshlrev_b32_e32 v180, 2, v135
	v_bfe_u32 v1, v134, 2, 2
	s_lshl_b32 s10, s17, 7
	v_or_b32_e32 v1, v180, v1
	v_or_b32_e32 v181, v101, v100
	s_mov_b32 s19, 0
	v_mul_u32_u24_e32 v182, 0x130, v1
	v_add_co_u32_e32 v28, vcc, s2, v8
	s_nop 1
	v_addc_co_u32_e32 v29, vcc, 0, v9, vcc
	v_add_co_u32_e32 v32, vcc, s2, v6
	global_load_dwordx4 v[28:31], v[28:29], off
	s_nop 0
	v_addc_co_u32_e32 v33, vcc, 0, v7, vcc
	v_add_co_u32_e32 v36, vcc, s2, v4
	global_load_dwordx4 v[32:35], v[32:33], off
	s_nop 0
	v_addc_co_u32_e32 v37, vcc, 0, v5, vcc
	v_add_co_u32_e32 v40, vcc, s2, v2
	global_load_dwordx4 v[36:39], v[36:37], off
	s_nop 0
	v_addc_co_u32_e32 v41, vcc, 0, v3, vcc
	global_load_dwordx4 v[40:43], v[40:41], off
	s_cmp_eq_u32 s6, 15
	s_waitcnt vmcnt(7)
	ds_write_b128 v26, v[10:13]
	s_waitcnt vmcnt(6)
	ds_write_b128 v27, v[14:17]
	s_waitcnt vmcnt(5)
	ds_write_b128 v26, v[18:21] offset:19456
	s_waitcnt vmcnt(4)
	ds_write_b128 v27, v[22:25] offset:19456
	s_waitcnt vmcnt(3)
	ds_write_b128 v26, v[28:31] offset:38912
	s_waitcnt vmcnt(2)
	ds_write_b128 v27, v[32:35] offset:38912
	s_waitcnt vmcnt(1)
	ds_write_b128 v26, v[36:39] offset:58368
	s_waitcnt vmcnt(0)
	ds_write_b128 v27, v[40:43] offset:58368
	v_mul_u32_u24_e32 v10, 0x130, v179
	v_add3_u32 v144, v0, v10, s10
	s_mov_b32 s10, 0
	s_waitcnt lgkmcnt(0)
	s_barrier
	s_cbranch_scc1 .LBB0_853
	v_add_co_u32_e32 v0, vcc, 0x40000, v8
	s_mov_b32 s11, 1
	s_nop 0
	v_addc_co_u32_e32 v1, vcc, 0, v9, vcc
	v_add_co_u32_e32 v6, vcc, 0x40000, v6
	s_lshl_b32 s19, s12, 1
	s_nop 0
	v_addc_co_u32_e32 v7, vcc, 0, v7, vcc
	global_load_dwordx4 v[80:83], v[0:1], off
	global_load_dwordx4 v[84:87], v[6:7], off
	v_add_co_u32_e32 v0, vcc, 0x40000, v4
	s_nop 1
	v_addc_co_u32_e32 v1, vcc, 0, v5, vcc
	v_add_co_u32_e32 v2, vcc, 0x40000, v2
	s_nop 1
	v_addc_co_u32_e32 v3, vcc, 0, v3, vcc
	global_load_dwordx4 v[88:91], v[0:1], off
	global_load_dwordx4 v[92:95], v[2:3], off
	v_add_u32_e32 v4, 0, v144
	ds_read_b128 v[0:3], v4
	ds_read_b128 v[32:35], v4 offset:32
	ds_read_b128 v[16:19], v4 offset:9728
	ds_read_b128 v[36:39], v4 offset:9760
	ds_read_b128 v[40:43], v4 offset:64
	ds_read_b128 v[44:47], v4 offset:96
	ds_read_b128 v[48:51], v4 offset:9792
	ds_read_b128 v[52:55], v4 offset:9824
	s_setprio 1
	s_waitcnt lgkmcnt(7)
	v_mfma_f32_32x32x16_bf16 v[0:15], v[0:3], v[172:175], 0
	s_waitcnt lgkmcnt(5)
	v_mfma_f32_32x32x16_bf16 v[16:31], v[16:19], v[172:175], 0
	v_mfma_f32_32x32x16_bf16 v[0:15], v[32:35], v[168:171], v[0:15]
	s_waitcnt lgkmcnt(4)
	v_mfma_f32_32x32x16_bf16 v[16:31], v[36:39], v[168:171], v[16:31]
	s_waitcnt lgkmcnt(3)
	v_mfma_f32_32x32x16_bf16 v[0:15], v[40:43], v[164:167], v[0:15]
	s_waitcnt lgkmcnt(1)
	v_mfma_f32_32x32x16_bf16 v[16:31], v[48:51], v[164:167], v[16:31]
	v_mfma_f32_32x32x16_bf16 v[0:15], v[44:47], v[160:163], v[0:15]
	s_waitcnt lgkmcnt(0)
; template <int VSTR, int NDVB> DI void pv64(f32x16 (&O)[NDVB], const lds8* vp, const bf16x8 (&P)[4]) {
;   bf16x8 f[2][NDVB];
; #pragma unroll
; DI float rowmax32(const f32x16& s0, const f32x16& s1) {
;   float a = fmaxf(fmaxf(s0[0], s0[1]), s1[0]), b = fmaxf(fmaxf(s0[2], s0[3]), s1[1]); a = fmaxf(fmaxf(a, s1[2]), s1[3]);
; #pragma unroll
;   for (int r = 4; r < 16; r += 4) { a = fmaxf(fmaxf(a, s0[r]), s0[r + 1]); b = fmaxf(fmaxf(b, s0[r + 2]), s0[r + 3]); a = fmaxf(fmaxf(a, s1[r]), s1[r + 1]); b = fmaxf(fmaxf(b, s1[r + 2]), s1[r + 3]); }
;   const float m = fmaxf(a, b);
;   return fmaxf(m, __shfl_xor(m, 32));
; }
; template <int NDVB, bool HAS_NEXT> DI void softmax_def(f32x16& sa0, f32x16& sa1, f32x16& sb0, f32x16& sb1, f32x16 (&O)[NDVB], float& muse, float& l, bool first, bf16x8 (&P)[4], bool check = true) {
;   float mx = 0.f;
;   if (check) mx = rowmax32(sa0, sa1);
;   if (check && (first || __any(mx > 8.f))) {
;     float dl = first ? mx : fmaxf(mx, 0.f);
;     if (mx < -1e29f) dl = 0.f;
;     const float alpha = __builtin_amdgcn_exp2f(-dl);
;     muse += dl; l *= alpha;
; #pragma unroll
;     for (int i = 0; i < 16; ++i) { sa0[i] -= dl; sa1[i] -= dl; }
;     if (HAS_NEXT) {
; #pragma unroll
;       for (int i = 0; i < 16; ++i) { sb0[i] -= dl; sb1[i] -= dl; }
;     }
; #pragma unroll
;     for (int d = 0; d < NDVB; ++d)
; #pragma unroll
;       for (int i = 0; i < 16; ++i) O[d][i] *= alpha;
;   }
;   float sum = 0.f;
; #pragma unroll
;   for (int i = 0; i < 16; ++i) { sa0[i] = __builtin_amdgcn_exp2f(sa0[i]); sum += sa0[i]; }
; #pragma unroll
;   for (int i = 0; i < 16; ++i) { sa1[i] = __builtin_amdgcn_exp2f(sa1[i]); sum += sa1[i]; }
;   l += sum;
;   u32x4 w;
;   w.x = cvtpk(sa0[0], sa0[1]); w.y = cvtpk(sa0[2], sa0[3]); w.z = cvtpk(sa0[4], sa0[5]); w.w = cvtpk(sa0[6], sa0[7]); P[0] = __builtin_bit_cast(bf16x8, w);
;   w.x = cvtpk(sa0[8], sa0[9]); w.y = cvtpk(sa0[10], sa0[11]); w.z = cvtpk(sa0[12], sa0[13]); w.w = cvtpk(sa0[14], sa0[15]); P[1] = __builtin_bit_cast(bf16x8, w);
;   w.x = cvtpk(sa1[0], sa1[1]); w.y = cvtpk(sa1[2], sa1[3]); w.z = cvtpk(sa1[4], sa1[5]); w.w = cvtpk(sa1[6], sa1[7]); P[2] = __builtin_bit_cast(bf16x8, w);
;   w.x = cvtpk(sa1[8], sa1[9]); w.y = cvtpk(sa1[10], sa1[11]); w.z = cvtpk(sa1[12], sa1[13]); w.w = cvtpk(sa1[14], sa1[15]); P[3] = __builtin_bit_cast(bf16x8, w);
; }
	v_mfma_f32_32x32x16_bf16 v[16:31], v[52:55], v[160:163], v[16:31]
	s_setprio 0
	s_nop 8
	v_max_f32_e32 v32, v1, v1
	v_max_f32_e32 v33, v0, v0
	v_max_f32_e32 v32, v33, v32
	v_max3_f32 v33, v2, v3, v17
	v_max3_f32 v32, v32, v16, v18
	v_max3_f32 v32, v32, v19, v4
	v_max3_f32 v33, v33, v6, v7
	v_max3_f32 v32, v32, v5, v20
	v_max3_f32 v33, v33, v22, v23
	v_max3_f32 v32, v32, v21, v8
	v_max3_f32 v33, v33, v10, v11
	v_max3_f32 v32, v32, v9, v24
	v_max3_f32 v33, v33, v26, v27
	v_max3_f32 v32, v32, v25, v12
	v_max3_f32 v33, v33, v14, v15
	v_max3_f32 v32, v32, v13, v28
	v_max3_f32 v33, v33, v30, v31
	v_and_b32_e32 v34, 64, v202
	v_max3_f32 v32, v32, v29, v33
	v_xor_b32_e32 v33, 32, v202
	v_add_u32_e32 v34, 64, v34
	v_cmp_lt_i32_e32 vcc, v33, v34
	v_add3_u32 v212, v181, v182, 0
	s_nop 0
	v_cndmask_b32_e32 v33, v202, v33, vcc
	v_lshlrev_b32_e32 v139, 2, v33
	v_mov_b32_e32 v33, v32
	s_nop 1
	v_permlane32_swap_b32_e32 v33, v32
	v_max_f32_e32 v32, v32, v33
	v_cmp_ngt_f32_e32 vcc, s85, v32
	s_nop 1
	v_cndmask_b32_e32 v145, 0, v32, vcc
	v_exp_f32_e64 v32, -v145
	v_sub_f32_e32 v16, v16, v145
	v_sub_f32_e32 v17, v17, v145
	v_sub_f32_e32 v18, v18, v145
	v_sub_f32_e32 v19, v19, v145
	v_mul_f32_e32 v64, 0, v32
	v_exp_f32_e32 v188, v16
	v_exp_f32_e32 v189, v17
	v_exp_f32_e32 v190, v18
	v_exp_f32_e32 v191, v19
	ds_read_b64_tr_b16 v[16:17], v212 offset:19456
	ds_read_b64_tr_b16 v[32:33], v212 offset:19520
	ds_read_b64_tr_b16 v[48:49], v212 offset:19584
	ds_read_b64_tr_b16 v[114:115], v212 offset:19648
	ds_read_b64_tr_b16 v[18:19], v212 offset:21888
	ds_read_b64_tr_b16 v[34:35], v212 offset:21952
	ds_read_b64_tr_b16 v[50:51], v212 offset:22016
	ds_read_b64_tr_b16 v[116:117], v212 offset:22080
	ds_read_b64_tr_b16 v[118:119], v212 offset:24320
	ds_read_b64_tr_b16 v[122:123], v212 offset:24384
	ds_read_b64_tr_b16 v[126:127], v212 offset:24448
	ds_read_b64_tr_b16 v[130:131], v212 offset:24512
	ds_read_b64_tr_b16 v[120:121], v212 offset:26752
	ds_read_b64_tr_b16 v[124:125], v212 offset:26816
	ds_read_b64_tr_b16 v[128:129], v212 offset:26880
	ds_read_b64_tr_b16 v[132:133], v212 offset:26944
	v_sub_f32_e32 v0, v0, v145
	v_sub_f32_e32 v1, v1, v145
	v_sub_f32_e32 v2, v2, v145
	v_sub_f32_e32 v3, v3, v145
	v_sub_f32_e32 v20, v20, v145
	v_sub_f32_e32 v21, v21, v145
	v_sub_f32_e32 v22, v22, v145
	v_sub_f32_e32 v23, v23, v145
	v_sub_f32_e32 v24, v24, v145
	v_sub_f32_e32 v25, v25, v145
	v_sub_f32_e32 v26, v26, v145
	v_sub_f32_e32 v27, v27, v145
	v_sub_f32_e32 v28, v28, v145
	v_sub_f32_e32 v29, v29, v145
	v_sub_f32_e32 v30, v30, v145
	v_sub_f32_e32 v31, v31, v145
	v_sub_f32_e32 v4, v4, v145
	v_sub_f32_e32 v5, v5, v145
	v_sub_f32_e32 v6, v6, v145
	v_sub_f32_e32 v7, v7, v145
	v_sub_f32_e32 v8, v8, v145
	v_sub_f32_e32 v9, v9, v145
	v_sub_f32_e32 v10, v10, v145
	v_sub_f32_e32 v11, v11, v145
	v_sub_f32_e32 v12, v12, v145
	v_sub_f32_e32 v13, v13, v145
	v_sub_f32_e32 v14, v14, v145
	v_sub_f32_e32 v15, v15, v145
	v_exp_f32_e32 v146, v0
	v_exp_f32_e32 v147, v1
	v_exp_f32_e32 v148, v2
	v_exp_f32_e32 v149, v3
	v_exp_f32_e32 v150, v4
	v_exp_f32_e32 v151, v5
	v_exp_f32_e32 v152, v6
	v_exp_f32_e32 v153, v7
	v_exp_f32_e32 v154, v8
	v_exp_f32_e32 v155, v9
	v_exp_f32_e32 v156, v10
	v_exp_f32_e32 v157, v11
	v_exp_f32_e32 v158, v12
	v_exp_f32_e32 v159, v13
	v_exp_f32_e32 v176, v14
	v_exp_f32_e32 v177, v15
	v_exp_f32_e32 v192, v20
	v_exp_f32_e32 v193, v21
	v_exp_f32_e32 v194, v22
	v_exp_f32_e32 v195, v23
	v_exp_f32_e32 v196, v24
	v_exp_f32_e32 v197, v25
	v_exp_f32_e32 v198, v26
	v_exp_f32_e32 v199, v27
	v_exp_f32_e32 v208, v28
	v_exp_f32_e32 v209, v29
	v_exp_f32_e32 v210, v30
	v_exp_f32_e32 v211, v31
	v_mov_b32_e32 v65, v64
	v_mov_b32_e32 v66, v64
	v_mov_b32_e32 v67, v64
	v_mov_b32_e32 v68, v64
	v_mov_b32_e32 v69, v64
	v_mov_b32_e32 v70, v64
	v_mov_b32_e32 v71, v64
	v_mov_b32_e32 v72, v64
	v_mov_b32_e32 v73, v64
	v_mov_b32_e32 v74, v64
	v_mov_b32_e32 v75, v64
	v_mov_b32_e32 v76, v64
	v_mov_b32_e32 v77, v64
	v_mov_b32_e32 v78, v64
	v_mov_b32_e32 v79, v64
	v_cvt_pk_bf16_f32 v140, v146, v147
	v_cvt_pk_bf16_f32 v141, v148, v149
	v_cmp_neq_f32_e32 vcc, 0, v145
	v_cvt_pk_bf16_f32 v102, v196, v197
	v_cvt_pk_bf16_f32 v103, v198, v199
	v_cvt_pk_bf16_f32 v104, v208, v209
	v_cvt_pk_bf16_f32 v105, v210, v211
	v_cvt_pk_bf16_f32 v106, v188, v189
	v_cvt_pk_bf16_f32 v107, v190, v191
	v_cvt_pk_bf16_f32 v108, v192, v193
	v_cvt_pk_bf16_f32 v109, v194, v195
	v_cvt_pk_bf16_f32 v110, v154, v155
	v_cvt_pk_bf16_f32 v111, v156, v157
	v_cvt_pk_bf16_f32 v112, v158, v159
	v_cvt_pk_bf16_f32 v113, v176, v177
	v_cvt_pk_bf16_f32 v142, v150, v151
	v_cvt_pk_bf16_f32 v143, v152, v153
	s_setprio 1
	s_waitcnt lgkmcnt(11)
	v_mfma_f32_32x32x16_bf16 v[0:15], v[16:19], v[140:143], v[64:79]
	s_waitcnt lgkmcnt(10)
	v_mfma_f32_32x32x16_bf16 v[16:31], v[32:35], v[140:143], v[64:79]
	s_waitcnt lgkmcnt(9)
	v_mfma_f32_32x32x16_bf16 v[32:47], v[48:51], v[140:143], v[64:79]
	v_mov_b64_e32 v[48:49], v[64:65]
	v_mov_b64_e32 v[50:51], v[66:67]
	v_mov_b64_e32 v[52:53], v[68:69]
	v_mov_b64_e32 v[54:55], v[70:71]
	v_mov_b64_e32 v[56:57], v[72:73]
	v_mov_b64_e32 v[58:59], v[74:75]
	v_mov_b64_e32 v[60:61], v[76:77]
	v_mov_b64_e32 v[62:63], v[78:79]
	s_waitcnt lgkmcnt(8)
	s_nop 0
	v_mfma_f32_32x32x16_bf16 v[48:63], v[114:117], v[140:143], v[48:63]
	s_setprio 0
	ds_read_b64_tr_b16 v[66:67], v212 offset:29184
	ds_read_b64_tr_b16 v[70:71], v212 offset:29248
	ds_read_b64_tr_b16 v[74:75], v212 offset:29312
	ds_read_b64_tr_b16 v[114:115], v212 offset:29376
	ds_read_b64_tr_b16 v[68:69], v212 offset:31616
	ds_read_b64_tr_b16 v[72:73], v212 offset:31680
	ds_read_b64_tr_b16 v[76:77], v212 offset:31744
	ds_read_b64_tr_b16 v[116:117], v212 offset:31808
	s_setprio 1
	s_waitcnt lgkmcnt(11)
; template <int VSTR, int NDVB> DI void pv64(f32x16 (&O)[NDVB], const lds8* vp, const bf16x8 (&P)[4]) {
;   bf16x8 f[2][NDVB];
; #pragma unroll
;   for (int d = 0; d < NDVB; ++d) { const s16x4 lo = trrd(vp + d * 64), hi = trrd(vp + 8 * VSTR + d * 64); f[0][d] = __builtin_shufflevector(lo, hi, 0, 1, 2, 3, 4, 5, 6, 7); }
; #pragma unroll
;   for (int kk = 0; kk < 4; ++kk) {
;     if (kk < 3) {
; #pragma unroll
;       for (int d = 0; d < NDVB; ++d) { const s16x4 lo = trrd(vp + (16 * (kk + 1)) * VSTR + d * 64), hi = trrd(vp + (16 * (kk + 1) + 8) * VSTR + d * 64);
;         f[(kk + 1) & 1][d] = __builtin_shufflevector(lo, hi, 0, 1, 2, 3, 4, 5, 6, 7); }
;     }
;     SBAR();
;     __builtin_amdgcn_s_setprio(1);
; #pragma unroll
;     for (int d = 0; d < NDVB; ++d) O[d] = MFMA32(f[kk & 1][d], P[kk], O[d]);
;     __builtin_amdgcn_s_setprio(0);
;     SBAR();
;   }
; }
; template <int NDVB, bool HAS_NEXT> DI void softmax_def(f32x16& sa0, f32x16& sa1, f32x16& sb0, f32x16& sb1, f32x16 (&O)[NDVB], float& muse, float& l, bool first, bf16x8 (&P)[4], bool check = true) {
;     ...
;   float sum = 0.f;
; #pragma unroll
;   for (int i = 0; i < 16; ++i) { sa0[i] = __builtin_amdgcn_exp2f(sa0[i]); sum += sa0[i]; }
; #pragma unroll
;   for (int i = 0; i < 16; ++i) { sa1[i] = __builtin_amdgcn_exp2f(sa1[i]); sum += sa1[i]; }
;   l += sum;
;   u32x4 w;
;   w.x = cvtpk(sa0[0], sa0[1]); w.y = cvtpk(sa0[2], sa0[3]); w.z = cvtpk(sa0[4], sa0[5]); w.w = cvtpk(sa0[6], sa0[7]); P[0] = __builtin_bit_cast(bf16x8, w);
;   w.x = cvtpk(sa0[8], sa0[9]); w.y = cvtpk(sa0[10], sa0[11]); w.z = cvtpk(sa0[12], sa0[13]); w.w = cvtpk(sa0[14], sa0[15]); P[1] = __builtin_bit_cast(bf16x8, w);
;   w.x = cvtpk(sa1[0], sa1[1]); w.y = cvtpk(sa1[2], sa1[3]); w.z = cvtpk(sa1[4], sa1[5]); w.w = cvtpk(sa1[6], sa1[7]); P[2] = __builtin_bit_cast(bf16x8, w);
;   w.x = cvtpk(sa1[8], sa1[9]); w.y = cvtpk(sa1[10], sa1[11]); w.z = cvtpk(sa1[12], sa1[13]); w.w = cvtpk(sa1[14], sa1[15]); P[3] = __builtin_bit_cast(bf16x8, w);
; }
; template <bool LOAD2, bool MASK>
; DI void da_step(lds8* lds, const DaCtx& cx, int t, const bf16x8 (&q)[4], f32x16 (&O)[4], float& muse, float& l, f32x16& negm) {
;   u32x4 kr0, kr1, vr0, vr1;
;   if (LOAD2) { const size_t ro = (size_t)(t + 2) * 64;
;     kr0 = *(const u32x4*)(cx.kg + (ro + cx.sr0) * DM + cx.sc0 * 8); kr1 = *(const u32x4*)(cx.kg + (ro + cx.sr1) * DM + cx.sc1 * 8);
	v_mfma_f32_32x32x16_bf16 v[0:15], v[118:121], v[110:113], v[0:15]
	s_waitcnt lgkmcnt(10)
	v_mfma_f32_32x32x16_bf16 v[16:31], v[122:125], v[110:113], v[16:31]
	s_waitcnt lgkmcnt(9)
	v_mfma_f32_32x32x16_bf16 v[32:47], v[126:129], v[110:113], v[32:47]
	s_waitcnt lgkmcnt(8)
	v_mfma_f32_32x32x16_bf16 v[48:63], v[130:133], v[110:113], v[48:63]
	s_setprio 0
	ds_read_b64_tr_b16 v[110:111], v212 offset:34048
	ds_read_b64_tr_b16 v[118:119], v212 offset:34112
	ds_read_b64_tr_b16 v[122:123], v212 offset:34176
	ds_read_b64_tr_b16 v[126:127], v212 offset:34240
	ds_read_b64_tr_b16 v[112:113], v212 offset:36480
	ds_read_b64_tr_b16 v[120:121], v212 offset:36544
	ds_read_b64_tr_b16 v[124:125], v212 offset:36608
	ds_read_b64_tr_b16 v[128:129], v212 offset:36672
	s_setprio 1
	s_waitcnt lgkmcnt(11)
	v_mfma_f32_32x32x16_bf16 v[0:15], v[66:69], v[106:109], v[0:15]
	s_waitcnt lgkmcnt(10)
	v_mfma_f32_32x32x16_bf16 v[16:31], v[70:73], v[106:109], v[16:31]
	s_waitcnt lgkmcnt(9)
	v_mfma_f32_32x32x16_bf16 v[32:47], v[74:77], v[106:109], v[32:47]
	s_waitcnt lgkmcnt(8)
	v_mfma_f32_32x32x16_bf16 v[48:63], v[114:117], v[106:109], v[48:63]
	s_setprio 0
	s_setprio 1
	s_waitcnt lgkmcnt(3)
	v_mfma_f32_32x32x16_bf16 v[0:15], v[110:113], v[102:105], v[0:15]
	s_waitcnt lgkmcnt(2)
	v_mfma_f32_32x32x16_bf16 v[16:31], v[118:121], v[102:105], v[16:31]
	s_waitcnt lgkmcnt(1)
	v_mfma_f32_32x32x16_bf16 v[32:47], v[122:125], v[102:105], v[32:47]
	s_waitcnt lgkmcnt(0)
	v_mfma_f32_32x32x16_bf16 v[48:63], v[126:129], v[102:105], v[48:63]
	s_setprio 0
	v_readlane_b32 s2, v255, 5
	v_mov_b32_e32 v67, v187
	s_cmp_lg_u64 vcc, 0
	v_add3_u32 v65, s2, v137, v186
	s_waitcnt vmcnt(3)
	ds_write_b128 v65, v[80:83]
	v_add3_u32 v65, s2, v138, v186
	v_readlane_b32 s2, v255, 6
	s_waitcnt vmcnt(2)
	ds_write_b128 v65, v[84:87]
	s_cselect_b64 s[12:13], -1, 0
	v_add3_u32 v65, s2, v137, v186
	s_waitcnt vmcnt(1)
	ds_write_b128 v65, v[88:91]
	v_add3_u32 v65, s2, v138, v186
	s_waitcnt vmcnt(0)
	ds_write_b128 v65, v[92:95]
	v_add_f32_e32 v65, 0, v146
	v_add_f32_e32 v65, v147, v65
	v_add_f32_e32 v65, v148, v65
	v_add_f32_e32 v65, v149, v65
	v_add_f32_e32 v65, v150, v65
	v_add_f32_e32 v65, v151, v65
	v_add_f32_e32 v65, v152, v65
	v_add_f32_e32 v65, v153, v65
	v_add_f32_e32 v65, v154, v65
	v_add_f32_e32 v65, v155, v65
	v_add_f32_e32 v65, v156, v65
	v_add_f32_e32 v65, v157, v65
	v_add_f32_e32 v65, v158, v65
	v_add_f32_e32 v65, v159, v65
	v_add_f32_e32 v65, v176, v65
	v_add_f32_e32 v65, v177, v65
	v_add_f32_e32 v65, v188, v65
	v_add_f32_e32 v65, v189, v65
	v_add_f32_e32 v65, v190, v65
	v_add_f32_e32 v65, v191, v65
	v_add_f32_e32 v65, v192, v65
	v_add_f32_e32 v65, v193, v65
	v_add_f32_e32 v65, v194, v65
	v_add_f32_e32 v65, v195, v65
	v_add_f32_e32 v65, v196, v65
	v_add_f32_e32 v65, v197, v65
	v_add_f32_e32 v65, v198, v65
	v_add_f32_e32 v65, v199, v65
	v_add_f32_e32 v65, v208, v65
	v_add_f32_e32 v65, v209, v65
	v_add_f32_e32 v65, v210, v65
	v_add_f32_e32 v66, v211, v65
	v_mov_b32_e32 v65, v145
	v_pk_add_f32 v[176:177], v[64:65], v[66:67]
	s_lshl_b32 s6, s6, 1
	v_cndmask_b32_e64 v64, 0, -v177, s[12:13]
	s_lshl_b32 s12, s20, 19
	s_and_b32 s13, s20, 7
	s_sub_i32 s6, 29, s6
	s_and_b32 s12, s12, 0x3c00000
	s_lshl_b32 s13, s13, 8
	s_add_u32 s13, s56, s13
	s_addc_u32 s20, s57, 0
	v_add_u32_e32 v80, v182, v100
	v_readlane_b32 s2, v255, 7
	s_add_u32 s12, s13, s12
	s_addc_u32 s13, s20, 0
	v_add3_u32 v140, v80, v101, s2
	v_readlane_b32 s2, v255, 8
	v_mov_b32_e32 v65, v64
	v_mov_b32_e32 v66, v64
	v_mov_b32_e32 v67, v64
	v_mov_b32_e32 v68, v64
	v_mov_b32_e32 v69, v64
	v_mov_b32_e32 v70, v64
	v_mov_b32_e32 v71, v64
	v_mov_b32_e32 v72, v64
	v_mov_b32_e32 v73, v64
	v_mov_b32_e32 v74, v64
	v_mov_b32_e32 v75, v64
	v_mov_b32_e32 v76, v64
	v_mov_b32_e32 v77, v64
	v_mov_b32_e32 v78, v64
	v_mov_b32_e32 v79, v64
	v_lshl_add_u64 v[130:131], s[12:13], 0, v[96:97]
	v_lshl_add_u64 v[132:133], s[12:13], 0, v[98:99]
	v_add_u32_e32 v141, s2, v144
	s_mov_b32 s12, 0
	s_waitcnt lgkmcnt(0)
	s_barrier
; DI float rowmax32(const f32x16& s0, const f32x16& s1) {
;   float a = fmaxf(fmaxf(s0[0], s0[1]), s1[0]), b = fmaxf(fmaxf(s0[2], s0[3]), s1[1]); a = fmaxf(fmaxf(a, s1[2]), s1[3]);
; #pragma unroll
;   for (int r = 4; r < 16; r += 4) { a = fmaxf(fmaxf(a, s0[r]), s0[r + 1]); b = fmaxf(fmaxf(b, s0[r + 2]), s0[r + 3]); a = fmaxf(fmaxf(a, s1[r]), s1[r + 1]); b = fmaxf(fmaxf(b, s1[r + 2]), s1[r + 3]); }
;   const float m = fmaxf(a, b);
;   return fmaxf(m, __shfl_xor(m, 32));
; }
; template <int NDVB, bool HAS_NEXT> DI void softmax_def(f32x16& sa0, f32x16& sa1, f32x16& sb0, f32x16& sb1, f32x16 (&O)[NDVB], float& muse, float& l, bool first, bf16x8 (&P)[4], bool check = true) {
;   float mx = 0.f;
;   if (check) mx = rowmax32(sa0, sa1);
;   if (check && (first || __any(mx > 8.f))) {
;     float dl = first ? mx : fmaxf(mx, 0.f);
;     if (mx < -1e29f) dl = 0.f;
;     const float alpha = __builtin_amdgcn_exp2f(-dl);
;     muse += dl; l *= alpha;
; #pragma unroll
;     for (int i = 0; i < 16; ++i) { sa0[i] -= dl; sa1[i] -= dl; }
;     if (HAS_NEXT) {
; #pragma unroll
;       for (int i = 0; i < 16; ++i) { sb0[i] -= dl; sb1[i] -= dl; }
;     }
; #pragma unroll
;     for (int d = 0; d < NDVB; ++d)
; #pragma unroll
;       for (int i = 0; i < 16; ++i) O[d][i] *= alpha;
;   }
; template <bool LOAD2, bool MASK>
; DI void da_step(lds8* lds, const DaCtx& cx, int t, const bf16x8 (&q)[4], f32x16 (&O)[4], float& muse, float& l, f32x16& negm) {
;   u32x4 kr0, kr1, vr0, vr1;
;   if (LOAD2) { const size_t ro = (size_t)(t + 2) * 64;
;     kr0 = *(const u32x4*)(cx.kg + (ro + cx.sr0) * DM + cx.sc0 * 8); kr1 = *(const u32x4*)(cx.kg + (ro + cx.sr1) * DM + cx.sc1 * 8);
;     vr0 = *(const u32x4*)(cx.vg + (ro + cx.sr0) * DM + cx.sc0 * 8); vr1 = *(const u32x4*)(cx.vg + (ro + cx.sr1) * DM + cx.sc1 * 8); }
;   SBAR();
;   const int st = t % 3, stn2 = (st == 0) ? 2 : st - 1;
;   const bool cur_live = !MASK || 64 * t <= cx.q0 + 32 * cx.qs + 31;
;   if (cur_live) {
;     f32x16 sa0, sa1, du0, du1;
;     qk64c<DA_KSTR>(sa0, sa1, lds + st * DA_STAGE + cx.koff, q, negm);
;     if (MASK) {
;       if (64 * t + 63 > cx.q0 + 32 * cx.qs) {
; #pragma unroll
;         for (int i = 0; i < 16; ++i) { const int key = 64 * t + crow(i, cx.h); if (key > cx.qpos) sa0[i] = NEG; if (key + 32 > cx.qpos) sa1[i] = NEG; }
;       }
;     }
;     bf16x8 P[4];
;     const float mprev = muse;
.LBB0_847:
	v_lshl_add_u64 v[80:81], v[130:131], 0, v[186:187]
	v_add_co_u32_e32 v82, vcc, s86, v80
	s_mul_hi_u32 s20, s11, 0xaaaaaaab
	s_nop 0
	v_addc_co_u32_e32 v83, vcc, 0, v81, vcc
	global_load_dwordx4 v[112:115], v[82:83], off
	v_lshl_add_u64 v[82:83], v[132:133], 0, v[186:187]
	v_add_co_u32_e32 v84, vcc, s86, v82
	s_lshr_b32 s21, s20, 1
	s_nop 0
	v_addc_co_u32_e32 v85, vcc, 0, v83, vcc
	v_add_co_u32_e32 v80, vcc, s87, v80
	global_load_dwordx4 v[116:119], v[84:85], off
	s_nop 0
	v_addc_co_u32_e32 v81, vcc, 0, v81, vcc
	global_load_dwordx4 v[120:123], v[80:81], off
	v_add_co_u32_e32 v80, vcc, s87, v82
	s_add_i32 s13, s12, 1
	s_nop 0
	v_addc_co_u32_e32 v81, vcc, 0, v83, vcc
	global_load_dwordx4 v[124:127], v[80:81], off
	s_mul_i32 s20, s21, 0xfffe3800
	v_add_u32_e32 v84, s20, v141
	ds_read_b128 v[80:83], v84
	ds_read_b128 v[146:149], v84 offset:32
	ds_read_b128 v[150:153], v84 offset:9728
	ds_read_b128 v[154:157], v84 offset:9760
	ds_read_b128 v[192:195], v84 offset:64
	ds_read_b128 v[196:199], v84 offset:96
	ds_read_b128 v[208:211], v84 offset:9792
	ds_read_b128 v[212:215], v84 offset:9824
	s_setprio 1
	s_waitcnt lgkmcnt(7)
	v_mfma_f32_32x32x16_bf16 v[96:111], v[80:83], v[172:175], v[64:79]
	s_waitcnt lgkmcnt(5)
	v_mfma_f32_32x32x16_bf16 v[80:95], v[150:153], v[172:175], v[64:79]
	v_mfma_f32_32x32x16_bf16 v[96:111], v[146:149], v[168:171], v[96:111]
	s_waitcnt lgkmcnt(4)
	v_mfma_f32_32x32x16_bf16 v[80:95], v[154:157], v[168:171], v[80:95]
	s_waitcnt lgkmcnt(3)
	v_mfma_f32_32x32x16_bf16 v[96:111], v[192:195], v[164:167], v[96:111]
	s_waitcnt lgkmcnt(1)
	v_mfma_f32_32x32x16_bf16 v[80:95], v[208:211], v[164:167], v[80:95]
	v_mfma_f32_32x32x16_bf16 v[96:111], v[196:199], v[160:163], v[96:111]
	s_waitcnt lgkmcnt(0)
	v_mfma_f32_32x32x16_bf16 v[80:95], v[212:215], v[160:163], v[80:95]
	s_setprio 0
	s_bitcmp1_b32 s13, 0
	s_cselect_b64 s[22:23], -1, 0
	s_and_b64 vcc, exec, s[22:23]
	s_cbranch_vccnz .LBB0_850
	s_nop 4
	v_max_f32_e32 v128, v97, v97
	v_max_f32_e32 v129, v96, v96
	v_max_f32_e32 v128, v129, v128
	v_max3_f32 v129, v98, v99, v81
	v_max3_f32 v128, v128, v80, v82
	v_max3_f32 v128, v128, v83, v100
	v_max3_f32 v129, v129, v102, v103
	v_max3_f32 v128, v128, v101, v84
	v_max3_f32 v129, v129, v86, v87
	v_max3_f32 v128, v128, v85, v104
	v_max3_f32 v129, v129, v106, v107
	v_max3_f32 v128, v128, v105, v88
	v_max3_f32 v129, v129, v90, v91
	v_max3_f32 v128, v128, v89, v108
	v_max3_f32 v129, v129, v110, v111
	v_max3_f32 v128, v128, v109, v92
	v_max3_f32 v129, v129, v94, v95
	v_max3_f32 v128, v128, v93, v129
	v_mov_b32_e32 v129, v128
	s_nop 1
	v_permlane32_swap_b32_e32 v129, v128
	v_max_f32_e32 v128, v128, v129
	v_cmp_lt_f32_e32 vcc, s7, v128
	s_cbranch_vccz .LBB0_850
	v_max_f32_e32 v129, v128, v128
	v_max_f32_e32 v129, 0, v129
	v_cmp_ngt_f32_e32 vcc, s85, v128
	s_nop 1
	v_cndmask_b32_e32 v143, 0, v129, vcc
	v_exp_f32_e64 v142, -v143
	v_sub_f32_e32 v111, v111, v143
	v_sub_f32_e32 v110, v110, v143
	v_sub_f32_e32 v109, v109, v143
	v_pk_add_f32 v[146:147], v[176:177], v[142:143]
	v_pk_mul_f32 v[128:129], v[176:177], v[142:143]
	v_sub_f32_e32 v108, v108, v143
	v_mov_b32_e32 v129, v147
	v_sub_f32_e32 v107, v107, v143
	v_sub_f32_e32 v106, v106, v143
	v_sub_f32_e32 v105, v105, v143
	v_sub_f32_e32 v104, v104, v143
	v_sub_f32_e32 v103, v103, v143
	v_sub_f32_e32 v102, v102, v143
	v_sub_f32_e32 v101, v101, v143
	v_sub_f32_e32 v100, v100, v143
	v_sub_f32_e32 v99, v99, v143
	v_sub_f32_e32 v98, v98, v143
	v_sub_f32_e32 v97, v97, v143
	v_sub_f32_e32 v96, v96, v143
	v_sub_f32_e32 v95, v95, v143
	v_sub_f32_e32 v94, v94, v143
	v_sub_f32_e32 v93, v93, v143
	v_sub_f32_e32 v92, v92, v143
	v_sub_f32_e32 v91, v91, v143
	v_sub_f32_e32 v90, v90, v143
	v_sub_f32_e32 v89, v89, v143
	v_sub_f32_e32 v88, v88, v143
	v_sub_f32_e32 v87, v87, v143
	v_sub_f32_e32 v86, v86, v143
	v_sub_f32_e32 v85, v85, v143
	v_sub_f32_e32 v84, v84, v143
	v_sub_f32_e32 v83, v83, v143
	v_sub_f32_e32 v82, v82, v143
	v_sub_f32_e32 v81, v81, v143
	v_sub_f32_e32 v80, v80, v143
	v_pk_mul_f32 v[14:15], v[14:15], v[142:143] op_sel_hi:[1,0]
	v_pk_mul_f32 v[12:13], v[12:13], v[142:143] op_sel_hi:[1,0]
	v_pk_mul_f32 v[10:11], v[10:11], v[142:143] op_sel_hi:[1,0]
	v_pk_mul_f32 v[8:9], v[8:9], v[142:143] op_sel_hi:[1,0]
	v_pk_mul_f32 v[6:7], v[6:7], v[142:143] op_sel_hi:[1,0]
	v_pk_mul_f32 v[4:5], v[4:5], v[142:143] op_sel_hi:[1,0]
	v_pk_mul_f32 v[2:3], v[2:3], v[142:143] op_sel_hi:[1,0]
	v_pk_mul_f32 v[0:1], v[0:1], v[142:143] op_sel_hi:[1,0]
	v_pk_mul_f32 v[30:31], v[30:31], v[142:143] op_sel_hi:[1,0]
	v_pk_mul_f32 v[28:29], v[28:29], v[142:143] op_sel_hi:[1,0]
	v_pk_mul_f32 v[26:27], v[26:27], v[142:143] op_sel_hi:[1,0]
	v_pk_mul_f32 v[24:25], v[24:25], v[142:143] op_sel_hi:[1,0]
	v_pk_mul_f32 v[22:23], v[22:23], v[142:143] op_sel_hi:[1,0]
	v_pk_mul_f32 v[20:21], v[20:21], v[142:143] op_sel_hi:[1,0]
	v_pk_mul_f32 v[18:19], v[18:19], v[142:143] op_sel_hi:[1,0]
	v_pk_mul_f32 v[16:17], v[16:17], v[142:143] op_sel_hi:[1,0]
	v_pk_mul_f32 v[46:47], v[46:47], v[142:143] op_sel_hi:[1,0]
	v_pk_mul_f32 v[44:45], v[44:45], v[142:143] op_sel_hi:[1,0]
	v_pk_mul_f32 v[42:43], v[42:43], v[142:143] op_sel_hi:[1,0]
	v_pk_mul_f32 v[40:41], v[40:41], v[142:143] op_sel_hi:[1,0]
	v_pk_mul_f32 v[38:39], v[38:39], v[142:143] op_sel_hi:[1,0]
	v_pk_mul_f32 v[36:37], v[36:37], v[142:143] op_sel_hi:[1,0]
	v_pk_mul_f32 v[34:35], v[34:35], v[142:143] op_sel_hi:[1,0]
	v_pk_mul_f32 v[32:33], v[32:33], v[142:143] op_sel_hi:[1,0]
	v_pk_mul_f32 v[62:63], v[62:63], v[142:143] op_sel_hi:[1,0]
	v_pk_mul_f32 v[60:61], v[60:61], v[142:143] op_sel_hi:[1,0]
	v_pk_mul_f32 v[58:59], v[58:59], v[142:143] op_sel_hi:[1,0]
	v_pk_mul_f32 v[56:57], v[56:57], v[142:143] op_sel_hi:[1,0]
	v_pk_mul_f32 v[54:55], v[54:55], v[142:143] op_sel_hi:[1,0]
	v_pk_mul_f32 v[52:53], v[52:53], v[142:143] op_sel_hi:[1,0]
	v_pk_mul_f32 v[50:51], v[50:51], v[142:143] op_sel_hi:[1,0]
	v_pk_mul_f32 v[48:49], v[48:49], v[142:143] op_sel_hi:[1,0]
	s_branch .LBB0_851

; template <int MODE>
; DI void nsa_branch(lds8* lds, const bf16_t* kg, const bf16_t* vg, int pitch, unsigned tiles, const bf16x8 (&q)[4], int qpos, unsigned mybits, int blk,
;                    f32x16 (&O)[2], float& muse, float& l, int tid, int lane, int grp, CmpCap& cap) {
;   const int r = lane & 31, h = lane >> 5;
;   const int sr = tid >> 3, sc = tid & 7;
;   const int koff = r * NS_STR + h * 16;
;   const int voff = 64 * NS_STR + (4 * h + ((lane & 15) >> 2)) * NS_STR + ((lane >> 4) & 1) * 32 + (lane & 3) * 8;
;   volatile LAS int* jl = (volatile LAS int*)(lds + NS_LIST);
;   tiles = __builtin_amdgcn_readfirstlane(tiles);
;   const int ntl = __builtin_popcount(tiles);
;   if (tid < 32) { unsigned below = tiles & ((1u << tid) - 1u); if ((tiles >> tid) & 1u) jl[__builtin_popcount(below)] = tid; }
;   __syncthreads();
; #pragma unroll
;   for (int d = 0; d < 2; ++d)
; #pragma unroll
;     for (int i = 0; i < 16; ++i) O[d][i] = 0.f;
;   muse = 0.f; l = 0.f;
;   u32x4 kra, vra;
;     ...
;   NS_GLOAD(0, kra, vra); NS_LSTORE(0, kra, vra);
;   if (ntl > 1) { NS_GLOAD(1, kra, vra); NS_LSTORE(1, kra, vra); }
;   __syncthreads();
;   f32x16 s0, s1, du0, du1; bf16x8 P[4];
;   int st_cur = 0;
; DI void nsa_unit(const Params& p, lds8* lds, int bl, int g, int qb32) {
;   int tid = threadIdx.x; asm volatile("" : "+v"(tid));
;   const int lane = tid & 63, wid = __builtin_amdgcn_readfirstlane(tid >> 6);
;   unsigned char* ws = p.ws;
;   bf16_t* QNS = (bf16_t*)(ws + OFF_QNS); const bf16_t* KSW = (const bf16_t*)(ws + OFF_KSW); const bf16_t* VSW = (const bf16_t*)(ws + OFF_VSW);
;   const bf16_t* KC = (const bf16_t*)(ws + OFF_KC); const bf16_t* VC = (const bf16_t*)(ws + OFF_VC); const bf16_t* GNS = (const bf16_t*)(ws + OFF_GNS);
;   const float* rope = (const float*)(ws + OFF_ROPE);
;   const int r = lane & 31, h = lane >> 5; const int hh = g * 8 + wid;
;   const size_t rowbase = (size_t)bl * SEQ; const int q0 = qb32 * 32, qpos = q0 + r, blk = q0 >> 6;
;   bf16x8 qraw[4], qrot[4];
;   { const bf16_t* qp = QNS + (rowbase + qpos) * DM + hh * 64 + 8 * h;
; #pragma unroll
;     for (int ks = 0; ks < 4; ++ks) qraw[ks] = *(const bf16x8*)(qp + 16 * ks); }
;   const bf16_t* gp = GNS + (rowbase + qpos) * 64 + hh * 3;
;   const float g0 = bf2f(gp[0]), g1 = bf2f(gp[1]), g2 = bf2f(gp[2]);
;   f32x16 OT[2], O[2]; float m, l; const int grp = ((wid >> 2) ^ wid) & 1;
.LBB0_898:
	v_writelane_b32 v255, s88, 37
	s_movk_i32 s94, 0x84
	s_nop 0
	v_writelane_b32 v255, s89, 38
	s_or_b64 exec, exec, s[8:9]
	s_ashr_i32 s1, s0, 5
	v_mov_b32_e32 v136, v200
	s_sub_i32 s3, 63, s1
	s_bfe_u32 s71, s0, 0x40001
	s_and_b32 s70, s0, 1
	s_lshl_b32 s2, s3, 5
	v_readfirstlane_b32 s0, v136
	s_ashr_i32 s1, s0, 6
	v_and_b32_e32 v52, 31, v136
	s_lshl_b32 s0, s70, 3
	v_writelane_b32 v255, s1, 39
	s_add_i32 s0, s1, s0
	s_lshl_b32 s1, s71, 11
	v_or_b32_e32 v211, s2, v52
	v_add_u32_e32 v186, s1, v211
	v_readlane_b32 s8, v254, 51
	v_lshlrev_b64 v[0:1], 11, v[186:187]
	v_readlane_b32 s9, v254, 52
	s_lshl_b32 s96, s0, 6
	v_bfe_u32 v55, v136, 5, 1
	v_lshl_add_u64 v[0:1], s[8:9], 0, v[0:1]
	s_ashr_i32 s97, s96, 31
	v_lshl_add_u64 v[0:1], s[96:97], 1, v[0:1]
	v_lshlrev_b32_e32 v2, 4, v55
	v_mov_b32_e32 v3, v187
	v_lshl_add_u64 v[0:1], v[0:1], 0, v[2:3]
	v_readlane_b32 s8, v254, 57
	global_load_dwordx4 v[44:47], v[0:1], off
	global_load_dwordx4 v[36:39], v[0:1], off offset:32
	global_load_dwordx4 v[40:43], v[0:1], off offset:64
	global_load_dwordx4 v[32:35], v[0:1], off offset:96
	v_lshlrev_b64 v[0:1], 7, v[186:187]
	v_readlane_b32 s9, v254, 58
	v_writelane_b32 v255, s2, 40
	v_writelane_b32 v255, s1, 41
	v_lshl_add_u64 v[0:1], s[8:9], 0, v[0:1]
	s_mul_i32 s8, s0, 3
	s_ashr_i32 s9, s8, 31
	v_lshl_add_u64 v[0:1], s[8:9], 1, v[0:1]
	global_load_dword v209, v[0:1], off
	global_load_ushort v210, v[0:1], off offset:4
	v_cmp_gt_u32_e32 vcc, 2, v136
	s_and_saveexec_b64 s[8:9], vcc
	v_lshl_add_u32 v0, v136, 2, 0
	v_add_u32_e32 v0, 0x16d10, v0
	ds_write_b32 v0, v136
	s_or_b64 exec, exec, s[8:9]
	s_lshl_b32 s0, s70, 14
	s_lshl_b32 s6, s71, 15
	s_or_b32 s0, s6, s0
	v_readlane_b32 s1, v254, 55
	s_add_u32 s10, s1, s0
	v_readlane_b32 s1, v254, 56
	s_addc_u32 s11, s1, 0
	v_readlane_b32 s1, v254, 61
	v_and_b32_e32 v199, 63, v136
	s_add_u32 s8, s1, s0
	v_readlane_b32 s0, v254, 62
	s_addc_u32 s9, s0, 0
	v_lshlrev_b32_e32 v214, 2, v55
	v_lshrrev_b32_e32 v0, 2, v136
	v_lshlrev_b32_e32 v1, 3, v199
	s_add_i32 s0, 0, 0x16d10
	v_and_or_b32 v51, v0, 3, v214
	v_lshlrev_b32_e32 v0, 1, v199
	v_and_b32_e32 v1, 24, v1
	v_mov_b32_e32 v48, s0
	v_and_or_b32 v66, v0, 32, v1
	s_waitcnt lgkmcnt(0)
	s_barrier
	v_readlane_b32 s2, v255, 9
	ds_read_b32 v0, v48
	v_ashrrev_i32_e32 v212, 3, v136
	v_and_b32_e32 v54, 7, v136
	v_mov_b32_e32 v50, s2
	ds_read_b32 v9, v50
	v_lshlrev_b32_e32 v192, 4, v54
	v_mov_b32_e32 v193, v187
	s_movk_i32 s1, 0x90
	v_mul_lo_u32 v8, v212, s1
	v_mul_u32_u24_e32 v208, 0x90, v52
	v_lshl_add_u32 v213, v55, 4, v208
	s_waitcnt lgkmcnt(0)
	v_readfirstlane_b32 s6, v0
	v_readfirstlane_b32 s77, v9
	v_add3_u32 v215, 0, v8, v192
	s_nop 0
	v_lshl_add_u32 v0, s6, 6, v212
	s_nop 0
	v_lshl_add_u32 v10, s77, 6, v212
	v_ashrrev_i32_e32 v1, 31, v0
	v_ashrrev_i32_e32 v11, 31, v10
	v_lshlrev_b64 v[4:5], 7, v[0:1]
	v_lshlrev_b64 v[12:13], 7, v[10:11]
	v_lshl_add_u64 v[0:1], s[10:11], 0, v[4:5]
	v_lshl_add_u64 v[0:1], v[0:1], 0, v[192:193]
	v_lshl_add_u64 v[4:5], s[8:9], 0, v[4:5]
	global_load_dwordx4 v[0:3], v[0:1], off
	v_lshl_add_u64 v[4:5], v[4:5], 0, v[192:193]
	global_load_dwordx4 v[4:7], v[4:5], off
	v_lshl_add_u64 v[8:9], s[10:11], 0, v[12:13]
	v_lshl_add_u64 v[8:9], v[8:9], 0, v[192:193]
	v_lshl_add_u64 v[12:13], s[8:9], 0, v[12:13]
	global_load_dwordx4 v[8:11], v[8:9], off
	v_lshl_add_u64 v[12:13], v[12:13], 0, v[192:193]
	global_load_dwordx4 v[12:15], v[12:13], off
	s_waitcnt vmcnt(3)
	ds_write_b128 v215, v[0:3]
	s_waitcnt vmcnt(2)
	ds_write_b128 v215, v[4:7] offset:9216
	s_waitcnt vmcnt(1)
	ds_write_b128 v215, v[8:11] offset:18432
	s_waitcnt vmcnt(0)
	ds_write_b128 v215, v[12:15] offset:27648
	v_subrev_u32_e32 v0, 31, v211
	v_and_b32_e32 v1, 64, v202
	v_ashrrev_i32_e32 v121, 4, v0
	v_xor_b32_e32 v0, 32, v202
	v_add_u32_e32 v53, 64, v1
	v_cmp_lt_i32_e32 vcc, v0, v53
	s_waitcnt lgkmcnt(0)
	s_barrier
	v_cndmask_b32_e32 v0, v202, v0, vcc
	v_lshlrev_b32_e32 v193, 2, v0
	v_add_u32_e32 v134, 0, v213
	ds_read_b128 v[56:59], v134
	ds_read_b128 v[60:63], v134 offset:32
	ds_read_b128 v[68:71], v134 offset:4608
	ds_read_b128 v[72:75], v134 offset:4640
	ds_read_b128 v[76:79], v134 offset:64
	ds_read_b128 v[80:83], v134 offset:96
	ds_read_b128 v[84:87], v134 offset:4672
	ds_read_b128 v[88:91], v134 offset:4704
	s_setprio 1
	s_mov_b32 s77, s76
	s_mov_b32 s78, s76
	s_mov_b32 s79, s76
	s_mov_b32 s80, s76
	s_mov_b32 s81, s76
	s_mov_b32 s82, s76
	s_mov_b32 s83, s76
	s_mov_b32 s84, s76
	s_mov_b32 s85, s76
	s_mov_b32 s86, s76
	s_mov_b32 s87, s76
	s_mov_b32 s88, s76
	s_mov_b32 s89, s76
	s_mov_b32 s90, s76
	s_mov_b32 s91, s76
	v_mov_b64_e32 v[0:1], s[76:77]
	v_mov_b64_e32 v[2:3], s[78:79]
	v_mov_b64_e32 v[4:5], s[80:81]
	v_mov_b64_e32 v[6:7], s[82:83]
	v_mov_b64_e32 v[8:9], s[84:85]
	v_mov_b64_e32 v[10:11], s[86:87]
	v_mov_b64_e32 v[12:13], s[88:89]
	v_mov_b64_e32 v[14:15], s[90:91]
	s_waitcnt lgkmcnt(7)
	s_nop 0
	v_mfma_f32_32x32x16_bf16 v[16:31], v[56:59], v[44:47], v[0:15]
	s_waitcnt lgkmcnt(5)
	v_mfma_f32_32x32x16_bf16 v[0:15], v[68:71], v[44:47], v[0:15]
	v_mfma_f32_32x32x16_bf16 v[16:31], v[60:63], v[36:39], v[16:31]
	s_waitcnt lgkmcnt(4)
	v_mfma_f32_32x32x16_bf16 v[0:15], v[72:75], v[36:39], v[0:15]
	s_waitcnt lgkmcnt(3)
	v_mfma_f32_32x32x16_bf16 v[16:31], v[76:79], v[40:43], v[16:31]
	s_waitcnt lgkmcnt(1)
	v_mfma_f32_32x32x16_bf16 v[0:15], v[84:87], v[40:43], v[0:15]
	v_mfma_f32_32x32x16_bf16 v[16:31], v[80:83], v[32:35], v[16:31]
	s_waitcnt lgkmcnt(0)
	v_mfma_f32_32x32x16_bf16 v[0:15], v[88:91], v[32:35], v[0:15]
	s_setprio 0
	ds_read_b32 v48, v48
	s_mov_b32 s85, 0xefa18f08
	v_mad_u32_u24 v216, v51, s1, v66
	v_add_u32_e32 v96, 0, v216
	s_waitcnt lgkmcnt(0)
; #define LAS __attribute__((address_space(3)))
; DI float rowmax32(const f32x16& s0, const f32x16& s1) {
;   float a = fmaxf(fmaxf(s0[0], s0[1]), s1[0]), b = fmaxf(fmaxf(s0[2], s0[3]), s1[1]); a = fmaxf(fmaxf(a, s1[2]), s1[3]);
; #pragma unroll
;   for (int r = 4; r < 16; r += 4) { a = fmaxf(fmaxf(a, s0[r]), s0[r + 1]); b = fmaxf(fmaxf(b, s0[r + 2]), s0[r + 3]); a = fmaxf(fmaxf(a, s1[r]), s1[r + 1]); b = fmaxf(fmaxf(b, s1[r + 2]), s1[r + 3]); }
;   const float m = fmaxf(a, b);
;   return fmaxf(m, __shfl_xor(m, 32));
; }
; template <int NDVB, bool HAS_NEXT> DI void softmax_def(f32x16& sa0, f32x16& sa1, f32x16& sb0, f32x16& sb1, f32x16 (&O)[NDVB], float& muse, float& l, bool first, bf16x8 (&P)[4], bool check = true) {
;   float mx = 0.f;
;   if (check) mx = rowmax32(sa0, sa1);
;   if (check && (first || __any(mx > 8.f))) {
;     float dl = first ? mx : fmaxf(mx, 0.f);
;     if (mx < -1e29f) dl = 0.f;
;     const float alpha = __builtin_amdgcn_exp2f(-dl);
;     muse += dl; l *= alpha;
; #pragma unroll
;     for (int i = 0; i < 16; ++i) { sa0[i] -= dl; sa1[i] -= dl; }
;     if (HAS_NEXT) {
; #pragma unroll
;       for (int i = 0; i < 16; ++i) { sb0[i] -= dl; sb1[i] -= dl; }
;     }
; #pragma unroll
;     for (int d = 0; d < NDVB; ++d)
; #pragma unroll
;       for (int i = 0; i < 16; ++i) O[d][i] *= alpha;
;   }
;   float sum = 0.f;
; #pragma unroll
;   for (int i = 0; i < 16; ++i) { sa0[i] = __builtin_amdgcn_exp2f(sa0[i]); sum += sa0[i]; }
; #pragma unroll
;   for (int i = 0; i < 16; ++i) { sa1[i] = __builtin_amdgcn_exp2f(sa1[i]); sum += sa1[i]; }
; template <int MODE, int SLOT> DI void ns_valu(volatile LAS int* jl, int t, int ntl, int qpos, int h, int blk, f32x16& s0, f32x16& s1, f32x16& du0, f32x16& du1, f32x16 (&O)[2], float& muse, float& l, bf16x8 (&P)[4], CmpCap& cap) {
;     if (t < ntl) {
;       const int j = __builtin_amdgcn_readfirstlane(jl[t]);
;       if (MODE == 0) {
;         const int lim = ((qpos - 31) >> 4) - 64 * j - 4 * h;
; #pragma unroll
;         for (int i = 0; i < 16; ++i) { const int ci = (i & 3) + 8 * (i >> 2); if (ci > lim) s0[i] = NEG; if (ci + 32 > lim) s1[i] = NEG; }
	v_readfirstlane_b32 s6, v48
	s_nop 1
	v_lshl_or_b32 v48, s6, 6, v214
	v_sub_u32_e32 v48, v121, v48
	v_cmp_gt_i32_e64 s[64:65], 26, v48
	v_cmp_gt_i32_e64 s[68:69], 27, v48
	v_cmp_gt_i32_e64 s[60:61], 25, v48
	s_and_b64 s[64:65], s[68:69], s[64:65]
	v_cmp_gt_i32_e64 s[56:57], 24, v48
	s_and_b64 s[60:61], s[64:65], s[60:61]
	v_cmp_gt_i32_e64 s[52:53], 19, v48
	s_and_b64 s[56:57], s[60:61], s[56:57]
	v_cmp_gt_i32_e64 s[48:49], 18, v48
	s_and_b64 s[52:53], s[56:57], s[52:53]
	v_cmp_gt_i32_e64 s[44:45], 17, v48
	s_and_b64 s[48:49], s[52:53], s[48:49]
	v_cmp_gt_i32_e64 s[40:41], 16, v48
	s_and_b64 s[44:45], s[48:49], s[44:45]
	v_cmp_gt_i32_e64 s[36:37], 11, v48
	s_and_b64 s[40:41], s[44:45], s[40:41]
	v_cmp_gt_i32_e64 s[30:31], 10, v48
	s_and_b64 s[36:37], s[40:41], s[36:37]
	v_cmp_gt_i32_e64 s[26:27], 9, v48
	s_and_b64 s[30:31], s[36:37], s[30:31]
	v_cmp_gt_i32_e64 s[22:23], 8, v48
	s_and_b64 s[26:27], s[30:31], s[26:27]
	v_cmp_gt_i32_e64 s[20:21], 3, v48
	s_and_b64 s[22:23], s[26:27], s[22:23]
	v_cmp_gt_i32_e64 s[18:19], 2, v48
	s_and_b64 s[20:21], s[22:23], s[20:21]
	v_cmp_gt_i32_e64 s[16:17], 1, v48
	s_and_b64 s[18:19], s[20:21], s[18:19]
	v_cmp_gt_i32_e64 s[14:15], 0, v48
	s_and_b64 s[16:17], s[18:19], s[16:17]
	s_and_b64 s[14:15], s[16:17], s[14:15]
	v_cmp_gt_i32_e64 s[66:67], 58, v48
	v_cndmask_b32_e64 v16, v16, v207, s[14:15]
	v_cmp_gt_i32_e64 s[14:15], 59, v48
	v_cmp_gt_i32_e64 s[62:63], 57, v48
	v_cmp_gt_i32_e64 s[58:59], 56, v48
	v_cndmask_b32_e64 v15, v15, v207, s[14:15]
	s_and_b64 s[14:15], s[14:15], s[66:67]
	v_cndmask_b32_e64 v14, v14, v207, s[14:15]
	s_and_b64 s[14:15], s[14:15], s[62:63]
	v_cmp_gt_i32_e64 s[54:55], 51, v48
	v_cndmask_b32_e64 v13, v13, v207, s[14:15]
	s_and_b64 s[14:15], s[14:15], s[58:59]
	v_cmp_gt_i32_e64 s[50:51], 50, v48
	v_cndmask_b32_e64 v12, v12, v207, s[14:15]
	s_and_b64 s[14:15], s[14:15], s[54:55]
	v_cmp_gt_i32_e64 s[46:47], 49, v48
	v_cndmask_b32_e64 v11, v11, v207, s[14:15]
	s_and_b64 s[14:15], s[14:15], s[50:51]
	v_cmp_gt_i32_e64 s[42:43], 48, v48
	v_cndmask_b32_e64 v10, v10, v207, s[14:15]
	s_and_b64 s[14:15], s[14:15], s[46:47]
	v_cmp_gt_i32_e64 s[38:39], 43, v48
	v_cndmask_b32_e64 v9, v9, v207, s[14:15]
	s_and_b64 s[14:15], s[14:15], s[42:43]
	v_cmp_gt_i32_e64 s[34:35], 42, v48
	v_cndmask_b32_e64 v8, v8, v207, s[14:15]
	s_and_b64 s[14:15], s[14:15], s[38:39]
	v_cmp_gt_i32_e64 s[28:29], 41, v48
	v_cndmask_b32_e64 v7, v7, v207, s[14:15]
	s_and_b64 s[14:15], s[14:15], s[34:35]
	v_cmp_gt_i32_e64 s[24:25], 40, v48
	v_cndmask_b32_e64 v6, v6, v207, s[14:15]
	s_and_b64 s[14:15], s[14:15], s[28:29]
	v_cmp_gt_i32_e64 s[12:13], 35, v48
	v_cndmask_b32_e64 v5, v5, v207, s[14:15]
	s_and_b64 s[14:15], s[14:15], s[24:25]
	v_cmp_gt_i32_e64 s[10:11], 34, v48
	s_and_b64 s[12:13], s[14:15], s[12:13]
	v_cmp_gt_i32_e64 s[8:9], 33, v48
	s_and_b64 s[10:11], s[12:13], s[10:11]
	v_cmp_gt_i32_e32 vcc, 32, v48
	v_cndmask_b32_e64 v17, v17, v207, s[16:17]
	s_and_b64 s[8:9], s[10:11], s[8:9]
	s_and_b64 vcc, s[8:9], vcc
	v_max_f32_e32 v48, v17, v17
	v_max_f32_e32 v49, v16, v16
	v_cndmask_b32_e64 v19, v19, v207, s[20:21]
	v_cndmask_b32_e64 v18, v18, v207, s[18:19]
	v_cndmask_b32_e64 v2, v2, v207, s[10:11]
	v_cndmask_b32_e64 v1, v1, v207, s[8:9]
	v_cndmask_b32_e32 v0, v0, v207, vcc
	v_max_f32_e32 v48, v49, v48
	v_cndmask_b32_e64 v23, v23, v207, s[36:37]
	v_cndmask_b32_e64 v22, v22, v207, s[30:31]
	v_cndmask_b32_e64 v20, v20, v207, s[22:23]
	v_cndmask_b32_e64 v3, v3, v207, s[12:13]
	v_max3_f32 v49, v18, v19, v1
	v_max3_f32 v48, v48, v0, v2
	v_cndmask_b32_e64 v21, v21, v207, s[26:27]
	v_cndmask_b32_e64 v4, v4, v207, s[14:15]
	v_max3_f32 v48, v48, v3, v20
	v_max3_f32 v49, v49, v22, v23
	v_cndmask_b32_e64 v27, v27, v207, s[52:53]
	v_cndmask_b32_e64 v26, v26, v207, s[48:49]
	v_cndmask_b32_e64 v24, v24, v207, s[40:41]
	v_max3_f32 v48, v48, v21, v4
	v_max3_f32 v49, v49, v6, v7
	v_cndmask_b32_e64 v25, v25, v207, s[44:45]
	v_max3_f32 v48, v48, v5, v24
	v_max3_f32 v49, v49, v26, v27
	v_cndmask_b32_e64 v31, v31, v207, s[68:69]
	v_cndmask_b32_e64 v30, v30, v207, s[64:65]
	v_cndmask_b32_e64 v28, v28, v207, s[56:57]
	v_max3_f32 v48, v48, v25, v8
	v_max3_f32 v49, v49, v10, v11
	v_cndmask_b32_e64 v29, v29, v207, s[60:61]
	v_max3_f32 v48, v48, v9, v28
	v_max3_f32 v49, v49, v30, v31
	v_max3_f32 v48, v48, v29, v12
	v_max3_f32 v49, v49, v14, v15
	v_max3_f32 v48, v48, v13, v49
	v_mov_b32_e32 v49, v48
	s_nop 1
	v_permlane32_swap_b32_e32 v49, v48
	v_max_f32_e32 v48, v48, v49
	v_cmp_ngt_f32_e32 vcc, s85, v48
	s_nop 1
	v_cndmask_b32_e32 v65, 0, v48, vcc
	v_sub_f32_e32 v16, v16, v65
	v_sub_f32_e32 v17, v17, v65
	v_exp_f32_e32 v97, v16
	v_sub_f32_e32 v18, v18, v65
	v_exp_f32_e32 v98, v17
	v_sub_f32_e32 v19, v19, v65
	v_exp_f32_e32 v99, v18
	v_sub_f32_e32 v20, v20, v65
	v_exp_f32_e32 v56, v19
	v_sub_f32_e32 v21, v21, v65
	v_add_f32_e32 v16, 0, v97
	v_exp_f32_e32 v100, v20
	v_sub_f32_e32 v22, v22, v65
	v_add_f32_e32 v16, v98, v16
	v_exp_f32_e32 v101, v21
	v_sub_f32_e32 v23, v23, v65
	v_add_f32_e32 v16, v99, v16
	v_exp_f32_e32 v102, v22
	v_sub_f32_e32 v24, v24, v65
	v_add_f32_e32 v16, v56, v16
	v_exp_f32_e32 v57, v23
	v_sub_f32_e32 v25, v25, v65
	v_add_f32_e32 v16, v100, v16
	v_exp_f32_e32 v103, v24
	v_sub_f32_e32 v26, v26, v65
	v_add_f32_e32 v16, v101, v16
	v_exp_f32_e32 v104, v25
	v_sub_f32_e32 v27, v27, v65
	v_add_f32_e32 v16, v102, v16
	v_exp_f32_e32 v105, v26
	v_sub_f32_e32 v28, v28, v65
	v_add_f32_e32 v16, v57, v16
	v_exp_f32_e32 v58, v27
	v_sub_f32_e32 v29, v29, v65
	v_add_f32_e32 v16, v103, v16
	v_exp_f32_e32 v106, v28
	v_sub_f32_e32 v30, v30, v65
	v_add_f32_e32 v16, v104, v16
	v_exp_f32_e32 v107, v29
	v_sub_f32_e32 v31, v31, v65
	v_add_f32_e32 v16, v105, v16
; DI unsigned cvtpk(float lo, float hi) { f32x2_t v = {lo, hi}; bf16x2_t b = __builtin_convertvector(v, bf16x2_t); return __builtin_bit_cast(unsigned, b); }
; #define MFMA32(a, b, c) __builtin_amdgcn_mfma_f32_32x32x16_bf16((a), (b), (c), 0, 0, 0)
; #define SBAR() __builtin_amdgcn_sched_barrier(0)
; template <int VSTR, int NDVB> DI void pv64(f32x16 (&O)[NDVB], const lds8* vp, const bf16x8 (&P)[4]) {
;   bf16x8 f[2][NDVB];
; #pragma unroll
;   for (int d = 0; d < NDVB; ++d) { const s16x4 lo = trrd(vp + d * 64), hi = trrd(vp + 8 * VSTR + d * 64); f[0][d] = __builtin_shufflevector(lo, hi, 0, 1, 2, 3, 4, 5, 6, 7); }
; #pragma unroll
;   for (int kk = 0; kk < 4; ++kk) {
;     if (kk < 3) {
; #pragma unroll
;       for (int d = 0; d < NDVB; ++d) { const s16x4 lo = trrd(vp + (16 * (kk + 1)) * VSTR + d * 64), hi = trrd(vp + (16 * (kk + 1) + 8) * VSTR + d * 64);
;         f[(kk + 1) & 1][d] = __builtin_shufflevector(lo, hi, 0, 1, 2, 3, 4, 5, 6, 7); }
;     }
;     SBAR();
;     __builtin_amdgcn_s_setprio(1);
; #pragma unroll
;     for (int d = 0; d < NDVB; ++d) O[d] = MFMA32(f[kk & 1][d], P[kk], O[d]);
;     __builtin_amdgcn_s_setprio(0);
;     SBAR();
;   }
; }
; template <int NDVB, bool HAS_NEXT> DI void softmax_def(f32x16& sa0, f32x16& sa1, f32x16& sb0, f32x16& sb1, f32x16 (&O)[NDVB], float& muse, float& l, bool first, bf16x8 (&P)[4], bool check = true) {
;     ...
;   float sum = 0.f;
; #pragma unroll
;   for (int i = 0; i < 16; ++i) { sa0[i] = __builtin_amdgcn_exp2f(sa0[i]); sum += sa0[i]; }
; #pragma unroll
;   for (int i = 0; i < 16; ++i) { sa1[i] = __builtin_amdgcn_exp2f(sa1[i]); sum += sa1[i]; }
;   l += sum;
;   u32x4 w;
;   w.x = cvtpk(sa0[0], sa0[1]); w.y = cvtpk(sa0[2], sa0[3]); w.z = cvtpk(sa0[4], sa0[5]); w.w = cvtpk(sa0[6], sa0[7]); P[0] = __builtin_bit_cast(bf16x8, w);
;   w.x = cvtpk(sa0[8], sa0[9]); w.y = cvtpk(sa0[10], sa0[11]); w.z = cvtpk(sa0[12], sa0[13]); w.w = cvtpk(sa0[14], sa0[15]); P[1] = __builtin_bit_cast(bf16x8, w);
;   w.x = cvtpk(sa1[0], sa1[1]); w.y = cvtpk(sa1[2], sa1[3]); w.z = cvtpk(sa1[4], sa1[5]); w.w = cvtpk(sa1[6], sa1[7]); P[2] = __builtin_bit_cast(bf16x8, w);
;   w.x = cvtpk(sa1[8], sa1[9]); w.y = cvtpk(sa1[10], sa1[11]); w.z = cvtpk(sa1[12], sa1[13]); w.w = cvtpk(sa1[14], sa1[15]); P[3] = __builtin_bit_cast(bf16x8, w);
	v_exp_f32_e32 v108, v30
	v_sub_f32_e32 v0, v0, v65
	v_add_f32_e32 v16, v58, v16
	v_exp_f32_e32 v59, v31
	v_sub_f32_e32 v1, v1, v65
	v_add_f32_e32 v16, v106, v16
	v_exp_f32_e32 v109, v0
	v_sub_f32_e32 v2, v2, v65
	v_add_f32_e32 v16, v107, v16
	v_exp_f32_e32 v110, v1
	v_sub_f32_e32 v3, v3, v65
	v_add_f32_e32 v16, v108, v16
	v_exp_f32_e32 v111, v2
	v_sub_f32_e32 v4, v4, v65
	v_add_f32_e32 v16, v59, v16
	v_exp_f32_e32 v60, v3
	v_sub_f32_e32 v5, v5, v65
	v_add_f32_e32 v0, v109, v16
	v_exp_f32_e32 v112, v4
	v_sub_f32_e32 v6, v6, v65
	v_add_f32_e32 v0, v110, v0
	v_exp_f32_e32 v113, v5
	v_sub_f32_e32 v7, v7, v65
	v_add_f32_e32 v0, v111, v0
	v_exp_f32_e32 v114, v6
	v_sub_f32_e32 v8, v8, v65
	v_add_f32_e32 v0, v60, v0
	v_exp_f32_e32 v61, v7
	v_sub_f32_e32 v9, v9, v65
	v_add_f32_e32 v0, v112, v0
	v_exp_f32_e32 v115, v8
	v_sub_f32_e32 v10, v10, v65
	v_sub_f32_e32 v12, v12, v65
	v_sub_f32_e32 v13, v13, v65
	v_sub_f32_e32 v14, v14, v65
	v_sub_f32_e32 v15, v15, v65
	v_add_f32_e32 v0, v113, v0
	v_exp_f32_e32 v116, v9
	v_sub_f32_e32 v11, v11, v65
	v_add_f32_e32 v0, v114, v0
	v_exp_f32_e32 v117, v10
	v_exp_f32_e32 v118, v12
	v_exp_f32_e32 v119, v13
	v_exp_f32_e32 v120, v14
	v_exp_f32_e32 v63, v15
	ds_read_b64_tr_b16 v[12:13], v96 offset:9216
	ds_read_b64_tr_b16 v[14:15], v96 offset:10368
	ds_read_b64_tr_b16 v[18:19], v96 offset:10432
	ds_read_b64_tr_b16 v[16:17], v96 offset:9280
	ds_read_b64_tr_b16 v[20:21], v96 offset:11520
	ds_read_b64_tr_b16 v[22:23], v96 offset:12672
	ds_read_b64_tr_b16 v[26:27], v96 offset:12736
	ds_read_b64_tr_b16 v[24:25], v96 offset:11584
	v_add_f32_e32 v0, v61, v0
	v_exp_f32_e32 v62, v11
	v_add_f32_e32 v0, v115, v0
	v_add_f32_e32 v0, v116, v0
	v_add_f32_e32 v0, v117, v0
	v_exp_f32_e64 v48, -v65
	v_add_f32_e32 v0, v62, v0
	v_add_f32_e32 v0, v118, v0
	v_add_f32_e32 v0, v119, v0
	v_add_f32_e32 v0, v120, v0
	v_mul_f32_e32 v64, 0, v48
	v_add_f32_e32 v186, v63, v0
	v_pk_add_f32 v[48:49], v[64:65], v[186:187]
	v_cvt_pk_bf16_f32 v0, v97, v98
	v_cvt_pk_bf16_f32 v2, v100, v101
	v_cvt_pk_bf16_f32 v3, v102, v57
	v_cvt_pk_bf16_f32 v4, v103, v104
	v_cvt_pk_bf16_f32 v5, v105, v58
	v_cvt_pk_bf16_f32 v6, v106, v107
	v_cvt_pk_bf16_f32 v7, v108, v59
	v_cvt_pk_bf16_f32 v8, v109, v110
	v_cvt_pk_bf16_f32 v9, v111, v60
	v_cvt_pk_bf16_f32 v10, v112, v113
	v_cvt_pk_bf16_f32 v11, v114, v61
	v_cvt_pk_bf16_f32 v28, v115, v116
	v_cvt_pk_bf16_f32 v29, v117, v62
	v_cvt_pk_bf16_f32 v30, v118, v119
	v_cvt_pk_bf16_f32 v31, v120, v63
	v_cvt_pk_bf16_f32 v1, v99, v56
	s_setprio 1
	v_mov_b32_e32 v65, v64
	v_mov_b32_e32 v66, v64
	v_mov_b32_e32 v67, v64
	v_mov_b32_e32 v68, v64
	v_mov_b32_e32 v69, v64
	v_mov_b32_e32 v70, v64
	v_mov_b32_e32 v71, v64
	v_mov_b32_e32 v72, v64
	v_mov_b32_e32 v73, v64
	v_mov_b32_e32 v74, v64
	v_mov_b32_e32 v75, v64
	v_mov_b32_e32 v76, v64
	v_mov_b32_e32 v77, v64
	v_mov_b32_e32 v78, v64
	v_mov_b32_e32 v79, v64
	s_waitcnt lgkmcnt(6)
	s_nop 0
	v_mfma_f32_32x32x16_bf16 v[80:95], v[12:15], v[0:3], v[64:79]
	s_waitcnt lgkmcnt(4)
	v_mfma_f32_32x32x16_bf16 v[64:79], v[16:19], v[0:3], v[64:79]
	s_setprio 0
	ds_read_b64_tr_b16 v[0:1], v96 offset:13824
	ds_read_b64_tr_b16 v[2:3], v96 offset:14976
	ds_read_b64_tr_b16 v[14:15], v96 offset:15040
	ds_read_b64_tr_b16 v[12:13], v96 offset:13888
	s_setprio 1
	s_waitcnt lgkmcnt(6)
	v_mfma_f32_32x32x16_bf16 v[80:95], v[20:23], v[4:7], v[80:95]
	s_waitcnt lgkmcnt(4)
	v_mfma_f32_32x32x16_bf16 v[64:79], v[24:27], v[4:7], v[64:79]
	s_setprio 0
	ds_read_b64_tr_b16 v[4:5], v96 offset:16128
	ds_read_b64_tr_b16 v[6:7], v96 offset:17280
	ds_read_b64_tr_b16 v[18:19], v96 offset:17344
	ds_read_b64_tr_b16 v[16:17], v96 offset:16192
	s_setprio 1
	s_waitcnt lgkmcnt(6)
	v_mfma_f32_32x32x16_bf16 v[80:95], v[0:3], v[8:11], v[80:95]
	s_waitcnt lgkmcnt(4)
	v_mfma_f32_32x32x16_bf16 v[64:79], v[12:15], v[8:11], v[64:79]
	s_setprio 0
	s_setprio 1
	s_waitcnt lgkmcnt(2)
	v_mfma_f32_32x32x16_bf16 v[80:95], v[4:7], v[28:31], v[80:95]
	s_waitcnt lgkmcnt(0)
	v_mfma_f32_32x32x16_bf16 v[64:79], v[16:19], v[28:31], v[64:79]
	s_setprio 0
	s_barrier
	ds_read_b128 v[122:125], v134 offset:18432
	ds_read_b128 v[126:129], v134 offset:18464
	ds_read_b128 v[130:133], v134 offset:23040
	ds_read_b128 v[138:141], v134 offset:23072
	ds_read_b128 v[142:145], v134 offset:18496
	ds_read_b128 v[146:149], v134 offset:18528
	ds_read_b128 v[150:153], v134 offset:23104
	ds_read_b128 v[154:157], v134 offset:23136
	v_xor_b32_e32 v0, 0x80000000, v49
	v_mov_b32_e32 v2, v0
	v_mov_b32_e32 v3, v0
	v_mov_b32_e32 v4, v0
	v_mov_b32_e32 v5, v0
	v_mov_b32_e32 v6, v0
	v_mov_b32_e32 v7, v0
	v_mov_b32_e32 v8, v0
	v_mov_b32_e32 v9, v0
	v_mov_b32_e32 v10, v0
	v_mov_b32_e32 v11, v0
	v_mov_b32_e32 v12, v0
	v_mov_b32_e32 v13, v0
	v_mov_b32_e32 v14, v0
	v_mov_b32_e32 v15, v0
	v_mov_b32_e32 v1, v0
	s_setprio 1
	s_waitcnt lgkmcnt(7)
	v_mfma_f32_32x32x16_bf16 v[16:31], v[122:125], v[44:47], v[0:15]
	s_waitcnt lgkmcnt(5)
	v_mfma_f32_32x32x16_bf16 v[0:15], v[130:133], v[44:47], v[0:15]
	v_mfma_f32_32x32x16_bf16 v[16:31], v[126:129], v[36:39], v[16:31]
	s_waitcnt lgkmcnt(4)
	v_mfma_f32_32x32x16_bf16 v[0:15], v[138:141], v[36:39], v[0:15]
	s_waitcnt lgkmcnt(3)
	v_mfma_f32_32x32x16_bf16 v[16:31], v[142:145], v[40:43], v[16:31]
	s_waitcnt lgkmcnt(1)
	v_mfma_f32_32x32x16_bf16 v[0:15], v[150:153], v[40:43], v[0:15]
	v_mfma_f32_32x32x16_bf16 v[16:31], v[146:149], v[32:35], v[16:31]
	s_waitcnt lgkmcnt(0)
	v_mfma_f32_32x32x16_bf16 v[0:15], v[154:157], v[32:35], v[0:15]
	s_setprio 0
	ds_read_b32 v50, v50
	s_waitcnt lgkmcnt(0)
; #define LAS __attribute__((address_space(3)))
; DI float rowmax32(const f32x16& s0, const f32x16& s1) {
;   float a = fmaxf(fmaxf(s0[0], s0[1]), s1[0]), b = fmaxf(fmaxf(s0[2], s0[3]), s1[1]); a = fmaxf(fmaxf(a, s1[2]), s1[3]);
; #pragma unroll
;   for (int r = 4; r < 16; r += 4) { a = fmaxf(fmaxf(a, s0[r]), s0[r + 1]); b = fmaxf(fmaxf(b, s0[r + 2]), s0[r + 3]); a = fmaxf(fmaxf(a, s1[r]), s1[r + 1]); b = fmaxf(fmaxf(b, s1[r + 2]), s1[r + 3]); }
;   const float m = fmaxf(a, b);
;   return fmaxf(m, __shfl_xor(m, 32));
; }
; template <int NDVB, bool HAS_NEXT> DI void softmax_def(f32x16& sa0, f32x16& sa1, f32x16& sb0, f32x16& sb1, f32x16 (&O)[NDVB], float& muse, float& l, bool first, bf16x8 (&P)[4], bool check = true) {
;   float mx = 0.f;
;   if (check) mx = rowmax32(sa0, sa1);
;   if (check && (first || __any(mx > 8.f))) {
;     float dl = first ? mx : fmaxf(mx, 0.f);
; template <int MODE, int SLOT> DI void ns_valu(volatile LAS int* jl, int t, int ntl, int qpos, int h, int blk, f32x16& s0, f32x16& s1, f32x16& du0, f32x16& du1, f32x16 (&O)[2], float& muse, float& l, bf16x8 (&P)[4], CmpCap& cap) {
;     if (t < ntl) {
;       const int j = __builtin_amdgcn_readfirstlane(jl[t]);
;       if (MODE == 0) {
;         const int lim = ((qpos - 31) >> 4) - 64 * j - 4 * h;
; #pragma unroll
;         for (int i = 0; i < 16; ++i) { const int ci = (i & 3) + 8 * (i >> 2); if (ci > lim) s0[i] = NEG; if (ci + 32 > lim) s1[i] = NEG; }
	v_readfirstlane_b32 s6, v50
	s_nop 1
	v_lshl_or_b32 v50, s6, 6, v214
	v_sub_u32_e32 v121, v121, v50
	v_cmp_gt_i32_e64 s[64:65], 26, v121
	v_cmp_gt_i32_e64 s[68:69], 27, v121
	v_cmp_gt_i32_e64 s[60:61], 25, v121
	s_and_b64 s[64:65], s[68:69], s[64:65]
	v_cmp_gt_i32_e64 s[56:57], 24, v121
	s_and_b64 s[60:61], s[64:65], s[60:61]
	v_cmp_gt_i32_e64 s[52:53], 19, v121
	s_and_b64 s[56:57], s[60:61], s[56:57]
	v_cmp_gt_i32_e64 s[48:49], 18, v121
	s_and_b64 s[52:53], s[56:57], s[52:53]
	v_cmp_gt_i32_e64 s[44:45], 17, v121
	s_and_b64 s[48:49], s[52:53], s[48:49]
	v_cmp_gt_i32_e64 s[40:41], 16, v121
	s_and_b64 s[44:45], s[48:49], s[44:45]
	v_cmp_gt_i32_e64 s[36:37], 11, v121
	s_and_b64 s[40:41], s[44:45], s[40:41]
	v_cmp_gt_i32_e64 s[30:31], 10, v121
	s_and_b64 s[36:37], s[40:41], s[36:37]
	v_cmp_gt_i32_e64 s[26:27], 9, v121
	s_and_b64 s[30:31], s[36:37], s[30:31]
	v_cmp_gt_i32_e64 s[22:23], 8, v121
	s_and_b64 s[26:27], s[30:31], s[26:27]
	v_cmp_gt_i32_e64 s[20:21], 3, v121
	s_and_b64 s[22:23], s[26:27], s[22:23]
	v_cmp_gt_i32_e64 s[18:19], 2, v121
	s_and_b64 s[20:21], s[22:23], s[20:21]
	v_cmp_gt_i32_e64 s[16:17], 1, v121
	s_and_b64 s[18:19], s[20:21], s[18:19]
	v_cmp_gt_i32_e64 s[14:15], 0, v121
	s_and_b64 s[16:17], s[18:19], s[16:17]
	s_and_b64 s[14:15], s[16:17], s[14:15]
	v_cmp_gt_i32_e64 s[66:67], 58, v121
	v_cndmask_b32_e64 v50, v16, v207, s[14:15]
	v_cmp_gt_i32_e64 s[14:15], 59, v121
	v_cmp_gt_i32_e64 s[62:63], 57, v121
	v_cmp_gt_i32_e64 s[58:59], 56, v121
	v_cndmask_b32_e64 v15, v15, v207, s[14:15]
	s_and_b64 s[14:15], s[14:15], s[66:67]
	v_cndmask_b32_e64 v14, v14, v207, s[14:15]
	s_and_b64 s[14:15], s[14:15], s[62:63]
	v_cmp_gt_i32_e64 s[54:55], 51, v121
	v_cndmask_b32_e64 v13, v13, v207, s[14:15]
	s_and_b64 s[14:15], s[14:15], s[58:59]
	v_cmp_gt_i32_e64 s[50:51], 50, v121
	v_cndmask_b32_e64 v12, v12, v207, s[14:15]
	s_and_b64 s[14:15], s[14:15], s[54:55]
	v_cmp_gt_i32_e64 s[46:47], 49, v121
	v_cndmask_b32_e64 v11, v11, v207, s[14:15]
	s_and_b64 s[14:15], s[14:15], s[50:51]
	v_cmp_gt_i32_e64 s[42:43], 48, v121
	v_cndmask_b32_e64 v10, v10, v207, s[14:15]
	s_and_b64 s[14:15], s[14:15], s[46:47]
	v_cmp_gt_i32_e64 s[38:39], 43, v121
	v_cndmask_b32_e64 v9, v9, v207, s[14:15]
	s_and_b64 s[14:15], s[14:15], s[42:43]
	v_cmp_gt_i32_e64 s[34:35], 42, v121
	v_cndmask_b32_e64 v8, v8, v207, s[14:15]
	s_and_b64 s[14:15], s[14:15], s[38:39]
	v_cmp_gt_i32_e64 s[28:29], 41, v121
	v_cndmask_b32_e64 v7, v7, v207, s[14:15]
	s_and_b64 s[14:15], s[14:15], s[34:35]
	v_cmp_gt_i32_e64 s[24:25], 40, v121
	v_cndmask_b32_e64 v6, v6, v207, s[14:15]
	s_and_b64 s[14:15], s[14:15], s[28:29]
	v_cmp_gt_i32_e64 s[12:13], 35, v121
	v_cndmask_b32_e64 v5, v5, v207, s[14:15]
	s_and_b64 s[14:15], s[14:15], s[24:25]
	v_cmp_gt_i32_e64 s[10:11], 34, v121
	s_and_b64 s[12:13], s[14:15], s[12:13]
	v_cmp_gt_i32_e64 s[8:9], 33, v121
	s_and_b64 s[10:11], s[12:13], s[10:11]
	v_cmp_gt_i32_e32 vcc, 32, v121
	s_and_b64 s[8:9], s[10:11], s[8:9]
	v_cndmask_b32_e64 v51, v17, v207, s[16:17]
	s_and_b64 vcc, s[8:9], vcc
	v_cndmask_b32_e64 v17, v1, v207, s[8:9]
	v_cndmask_b32_e32 v16, v0, v207, vcc
	v_max_f32_e32 v0, v51, v51
	v_max_f32_e32 v1, v50, v50
	v_cndmask_b32_e64 v19, v19, v207, s[20:21]
	v_cndmask_b32_e64 v18, v18, v207, s[18:19]
	v_cndmask_b32_e64 v2, v2, v207, s[10:11]
	v_max_f32_e32 v0, v1, v0
	v_cndmask_b32_e64 v23, v23, v207, s[36:37]
	v_cndmask_b32_e64 v22, v22, v207, s[30:31]
	v_cndmask_b32_e64 v20, v20, v207, s[22:23]
	v_cndmask_b32_e64 v3, v3, v207, s[12:13]
	v_max3_f32 v1, v18, v19, v17
	v_max3_f32 v0, v0, v16, v2
	v_cndmask_b32_e64 v21, v21, v207, s[26:27]
	v_cndmask_b32_e64 v4, v4, v207, s[14:15]
	v_max3_f32 v0, v0, v3, v20
	v_max3_f32 v1, v1, v22, v23
	v_cndmask_b32_e64 v27, v27, v207, s[52:53]
	v_cndmask_b32_e64 v26, v26, v207, s[48:49]
	v_cndmask_b32_e64 v24, v24, v207, s[40:41]
	v_max3_f32 v0, v0, v21, v4
	v_max3_f32 v1, v1, v6, v7
	v_cndmask_b32_e64 v25, v25, v207, s[44:45]
	v_max3_f32 v0, v0, v5, v24
	v_max3_f32 v1, v1, v26, v27
	v_cndmask_b32_e64 v31, v31, v207, s[68:69]
	v_cndmask_b32_e64 v30, v30, v207, s[64:65]
	v_cndmask_b32_e64 v28, v28, v207, s[56:57]
	v_max3_f32 v0, v0, v25, v8
	v_max3_f32 v1, v1, v10, v11
	v_cndmask_b32_e64 v29, v29, v207, s[60:61]
	v_max3_f32 v0, v0, v9, v28
	v_max3_f32 v1, v1, v30, v31
	v_max3_f32 v0, v0, v29, v12
	v_max3_f32 v1, v1, v14, v15
	v_max3_f32 v0, v0, v13, v1
	v_mov_b32_e32 v1, v0
	s_nop 1
	v_permlane32_swap_b32_e32 v1, v0
	v_max_f32_e32 v0, v0, v1
	v_cmp_lt_f32_e32 vcc, s7, v0
	s_cbranch_vccz .LBB0_902
; template <int NDVB, bool HAS_NEXT> DI void softmax_def(f32x16& sa0, f32x16& sa1, f32x16& sb0, f32x16& sb1, f32x16 (&O)[NDVB], float& muse, float& l, bool first, bf16x8 (&P)[4], bool check = true) {
;     ...
;   if (check && (first || __any(mx > 8.f))) {
;     float dl = first ? mx : fmaxf(mx, 0.f);
;     if (mx < -1e29f) dl = 0.f;
;     const float alpha = __builtin_amdgcn_exp2f(-dl);
;     muse += dl; l *= alpha;
; #pragma unroll
;     for (int i = 0; i < 16; ++i) { sa0[i] -= dl; sa1[i] -= dl; }
;     if (HAS_NEXT) {
; #pragma unroll
;       for (int i = 0; i < 16; ++i) { sb0[i] -= dl; sb1[i] -= dl; }
;     }
; #pragma unroll
;     for (int d = 0; d < NDVB; ++d)
; #pragma unroll
;       for (int i = 0; i < 16; ++i) O[d][i] *= alpha;
;   }
	v_max_f32_e32 v1, v0, v0
	v_max_f32_e32 v1, 0, v1
	v_cmp_ngt_f32_e32 vcc, s85, v0
	s_nop 1
	v_cndmask_b32_e32 v121, 0, v1, vcc
	v_exp_f32_e64 v122, -v121
	v_pk_add_f32 v[0:1], v[48:49], v[120:121]
	v_pk_mul_f32 v[78:79], v[78:79], v[122:123] op_sel_hi:[1,0]
	v_mov_b32_e32 v0, v121
	v_pk_add_f32 v[50:51], v[50:51], v[0:1] op_sel_hi:[1,0] neg_lo:[0,1] neg_hi:[0,1]
	v_pk_add_f32 v[16:17], v[16:17], v[0:1] op_sel_hi:[1,0] neg_lo:[0,1] neg_hi:[0,1]
	v_pk_add_f32 v[18:19], v[18:19], v[0:1] op_sel_hi:[1,0] neg_lo:[0,1] neg_hi:[0,1]
	v_pk_add_f32 v[2:3], v[2:3], v[0:1] op_sel_hi:[1,0] neg_lo:[0,1] neg_hi:[0,1]
	v_pk_add_f32 v[20:21], v[20:21], v[0:1] op_sel_hi:[1,0] neg_lo:[0,1] neg_hi:[0,1]
	v_pk_add_f32 v[4:5], v[4:5], v[0:1] op_sel_hi:[1,0] neg_lo:[0,1] neg_hi:[0,1]
	v_pk_add_f32 v[22:23], v[22:23], v[0:1] op_sel_hi:[1,0] neg_lo:[0,1] neg_hi:[0,1]
	v_pk_add_f32 v[6:7], v[6:7], v[0:1] op_sel_hi:[1,0] neg_lo:[0,1] neg_hi:[0,1]
	v_pk_add_f32 v[24:25], v[24:25], v[0:1] op_sel_hi:[1,0] neg_lo:[0,1] neg_hi:[0,1]
	v_pk_add_f32 v[8:9], v[8:9], v[0:1] op_sel_hi:[1,0] neg_lo:[0,1] neg_hi:[0,1]
	v_pk_add_f32 v[26:27], v[26:27], v[0:1] op_sel_hi:[1,0] neg_lo:[0,1] neg_hi:[0,1]
	v_pk_add_f32 v[10:11], v[10:11], v[0:1] op_sel_hi:[1,0] neg_lo:[0,1] neg_hi:[0,1]
	v_pk_add_f32 v[28:29], v[28:29], v[0:1] op_sel_hi:[1,0] neg_lo:[0,1] neg_hi:[0,1]
	v_pk_add_f32 v[12:13], v[12:13], v[0:1] op_sel_hi:[1,0] neg_lo:[0,1] neg_hi:[0,1]
	v_pk_add_f32 v[30:31], v[30:31], v[0:1] op_sel_hi:[1,0] neg_lo:[0,1] neg_hi:[0,1]
	v_pk_add_f32 v[14:15], v[14:15], v[0:1] op_sel_hi:[1,0] neg_lo:[0,1] neg_hi:[0,1]
	v_pk_mul_f32 v[76:77], v[76:77], v[122:123] op_sel_hi:[1,0]
	v_pk_mul_f32 v[74:75], v[74:75], v[122:123] op_sel_hi:[1,0]
	v_pk_mul_f32 v[72:73], v[72:73], v[122:123] op_sel_hi:[1,0]
	v_pk_mul_f32 v[70:71], v[70:71], v[122:123] op_sel_hi:[1,0]
	v_pk_mul_f32 v[68:69], v[68:69], v[122:123] op_sel_hi:[1,0]
	v_pk_mul_f32 v[66:67], v[66:67], v[122:123] op_sel_hi:[1,0]
	v_pk_mul_f32 v[64:65], v[64:65], v[122:123] op_sel_hi:[1,0]
	v_pk_mul_f32 v[94:95], v[94:95], v[122:123] op_sel_hi:[1,0]
	v_pk_mul_f32 v[92:93], v[92:93], v[122:123] op_sel_hi:[1,0]
	v_pk_mul_f32 v[90:91], v[90:91], v[122:123] op_sel_hi:[1,0]
	v_pk_mul_f32 v[88:89], v[88:89], v[122:123] op_sel_hi:[1,0]
	v_pk_mul_f32 v[86:87], v[86:87], v[122:123] op_sel_hi:[1,0]
	v_pk_mul_f32 v[84:85], v[84:85], v[122:123] op_sel_hi:[1,0]
	v_pk_mul_f32 v[82:83], v[82:83], v[122:123] op_sel_hi:[1,0]
	v_pk_mul_f32 v[80:81], v[80:81], v[122:123] op_sel_hi:[1,0]
	v_mul_f32_e32 v48, v48, v122
	s_branch .LBB0_903

; DI float rowmax32(const f32x16& s0, const f32x16& s1) {
;   float a = fmaxf(fmaxf(s0[0], s0[1]), s1[0]), b = fmaxf(fmaxf(s0[2], s0[3]), s1[1]); a = fmaxf(fmaxf(a, s1[2]), s1[3]);
; #pragma unroll
;   for (int r = 4; r < 16; r += 4) { a = fmaxf(fmaxf(a, s0[r]), s0[r + 1]); b = fmaxf(fmaxf(b, s0[r + 2]), s0[r + 3]); a = fmaxf(fmaxf(a, s1[r]), s1[r + 1]); b = fmaxf(fmaxf(b, s1[r + 2]), s1[r + 3]); }
;   const float m = fmaxf(a, b);
;   return fmaxf(m, __shfl_xor(m, 32));
; }
; template <int NDVB, bool HAS_NEXT> DI void softmax_def(f32x16& sa0, f32x16& sa1, f32x16& sb0, f32x16& sb1, f32x16 (&O)[NDVB], float& muse, float& l, bool first, bf16x8 (&P)[4], bool check = true) {
;   float mx = 0.f;
;   if (check) mx = rowmax32(sa0, sa1);
;   if (check && (first || __any(mx > 8.f))) {
;     float dl = first ? mx : fmaxf(mx, 0.f);
;     if (mx < -1e29f) dl = 0.f;
;     const float alpha = __builtin_amdgcn_exp2f(-dl);
;     muse += dl; l *= alpha;
; #pragma unroll
.LBB0_944:
	s_nop 6
	v_max_f32_e32 v96, v49, v49
	v_max_f32_e32 v97, v48, v48
	v_max_f32_e32 v96, v97, v96
	v_max3_f32 v97, v50, v51, v33
	v_max3_f32 v96, v96, v32, v34
	v_max3_f32 v96, v96, v35, v52
	v_max3_f32 v97, v97, v54, v55
	v_max3_f32 v96, v96, v53, v36
	v_max3_f32 v97, v97, v38, v39
	v_max3_f32 v96, v96, v37, v56
	v_max3_f32 v97, v97, v58, v59
	v_max3_f32 v96, v96, v57, v40
	v_max3_f32 v97, v97, v42, v43
	v_max3_f32 v96, v96, v41, v60
	v_max3_f32 v97, v97, v62, v63
	v_max3_f32 v96, v96, v61, v44
	v_max3_f32 v97, v97, v46, v47
	v_max3_f32 v96, v96, v45, v97
	v_mov_b32_e32 v97, v96
	s_cmp_lg_u32 s89, 3
	s_nop 1
	v_permlane32_swap_b32_e32 v97, v96
	v_max_f32_e32 v96, v96, v97
	s_cbranch_scc0 .LBB0_962
	v_cmp_lt_f32_e32 vcc, s7, v96
	s_mov_b64 s[86:87], 0
	s_mov_b64 s[84:85], 0
	s_cbranch_vccz .LBB0_947
	v_max_f32_e32 v97, v96, v96
	v_max_f32_e32 v97, 0, v97
	s_mov_b64 s[84:85], -1

; DI float rowmax32(const f32x16& s0, const f32x16& s1) {
;   float a = fmaxf(fmaxf(s0[0], s0[1]), s1[0]), b = fmaxf(fmaxf(s0[2], s0[3]), s1[1]); a = fmaxf(fmaxf(a, s1[2]), s1[3]);
; #pragma unroll
;   for (int r = 4; r < 16; r += 4) { a = fmaxf(fmaxf(a, s0[r]), s0[r + 1]); b = fmaxf(fmaxf(b, s0[r + 2]), s0[r + 3]); a = fmaxf(fmaxf(a, s1[r]), s1[r + 1]); b = fmaxf(fmaxf(b, s1[r + 2]), s1[r + 3]); }
;   const float m = fmaxf(a, b);
;   return fmaxf(m, __shfl_xor(m, 32));
; }
; template <int NDVB, bool HAS_NEXT> DI void softmax_def(f32x16& sa0, f32x16& sa1, f32x16& sb0, f32x16& sb1, f32x16 (&O)[NDVB], float& muse, float& l, bool first, bf16x8 (&P)[4], bool check = true) {
;   float mx = 0.f;
;   if (check) mx = rowmax32(sa0, sa1);
;   if (check && (first || __any(mx > 8.f))) {
;     float dl = first ? mx : fmaxf(mx, 0.f);
;     if (mx < -1e29f) dl = 0.f;
;     const float alpha = __builtin_amdgcn_exp2f(-dl);
;     muse += dl; l *= alpha;
; #pragma unroll
;     for (int i = 0; i < 16; ++i) { sa0[i] -= dl; sa1[i] -= dl; }
;     if (HAS_NEXT) {
; #pragma unroll
;       for (int i = 0; i < 16; ++i) { sb0[i] -= dl; sb1[i] -= dl; }
;     }
; #pragma unroll
;     for (int d = 0; d < NDVB; ++d)
; #pragma unroll
;       for (int i = 0; i < 16; ++i) O[d][i] *= alpha;
;   }
.LBB0_960:
	s_nop 6
	v_max_f32_e32 v32, v113, v113
	v_max_f32_e32 v33, v112, v112
	v_max_f32_e32 v32, v33, v32
	v_max3_f32 v33, v114, v115, v97
	v_max3_f32 v32, v32, v96, v98
	v_max3_f32 v32, v32, v99, v116
	v_max3_f32 v33, v33, v118, v119
	v_max3_f32 v32, v32, v117, v100
	v_max3_f32 v33, v33, v102, v103
	v_max3_f32 v32, v32, v101, v120
	v_max3_f32 v33, v33, v122, v123
	v_max3_f32 v32, v32, v121, v104
	v_max3_f32 v33, v33, v106, v107
	v_max3_f32 v32, v32, v105, v124
	v_max3_f32 v33, v33, v126, v127
	v_max3_f32 v32, v32, v125, v108
	v_max3_f32 v33, v33, v110, v111
	v_max3_f32 v32, v32, v109, v33
	v_mov_b32_e32 v33, v32
	s_nop 1
	v_permlane32_swap_b32_e32 v33, v32
	v_max_f32_e32 v32, v32, v33
	v_cmp_lt_f32_e32 vcc, s7, v32
	s_cbranch_vccz .LBB0_963
	v_max_f32_e32 v33, v32, v32
	v_max_f32_e32 v33, 0, v33
	v_cmp_ngt_f32_e32 vcc, s1, v32
	s_nop 1
	v_cndmask_b32_e32 v32, 0, v33, vcc
	v_exp_f32_e64 v142, -v32
	v_add_f32_e32 v138, v138, v32
	v_pk_add_f32 v[112:113], v[112:113], v[32:33] op_sel_hi:[1,0] neg_lo:[0,1] neg_hi:[0,1]
	v_pk_add_f32 v[96:97], v[96:97], v[32:33] op_sel_hi:[1,0] neg_lo:[0,1] neg_hi:[0,1]
	v_mul_f32_e32 v140, v139, v142
	v_pk_add_f32 v[114:115], v[114:115], v[32:33] op_sel_hi:[1,0] neg_lo:[0,1] neg_hi:[0,1]
	v_pk_add_f32 v[98:99], v[98:99], v[32:33] op_sel_hi:[1,0] neg_lo:[0,1] neg_hi:[0,1]
	v_pk_add_f32 v[116:117], v[116:117], v[32:33] op_sel_hi:[1,0] neg_lo:[0,1] neg_hi:[0,1]
	v_pk_add_f32 v[100:101], v[100:101], v[32:33] op_sel_hi:[1,0] neg_lo:[0,1] neg_hi:[0,1]
	v_pk_add_f32 v[118:119], v[118:119], v[32:33] op_sel_hi:[1,0] neg_lo:[0,1] neg_hi:[0,1]
	v_pk_add_f32 v[102:103], v[102:103], v[32:33] op_sel_hi:[1,0] neg_lo:[0,1] neg_hi:[0,1]
	v_pk_add_f32 v[120:121], v[120:121], v[32:33] op_sel_hi:[1,0] neg_lo:[0,1] neg_hi:[0,1]
	v_pk_add_f32 v[104:105], v[104:105], v[32:33] op_sel_hi:[1,0] neg_lo:[0,1] neg_hi:[0,1]
	v_pk_add_f32 v[122:123], v[122:123], v[32:33] op_sel_hi:[1,0] neg_lo:[0,1] neg_hi:[0,1]
	v_pk_add_f32 v[106:107], v[106:107], v[32:33] op_sel_hi:[1,0] neg_lo:[0,1] neg_hi:[0,1]
	v_pk_add_f32 v[124:125], v[124:125], v[32:33] op_sel_hi:[1,0] neg_lo:[0,1] neg_hi:[0,1]
	v_pk_add_f32 v[108:109], v[108:109], v[32:33] op_sel_hi:[1,0] neg_lo:[0,1] neg_hi:[0,1]
	v_pk_add_f32 v[126:127], v[126:127], v[32:33] op_sel_hi:[1,0] neg_lo:[0,1] neg_hi:[0,1]
	v_pk_add_f32 v[110:111], v[110:111], v[32:33] op_sel_hi:[1,0] neg_lo:[0,1] neg_hi:[0,1]
	v_pk_mul_f32 v[30:31], v[30:31], v[142:143] op_sel_hi:[1,0]
	v_pk_mul_f32 v[28:29], v[28:29], v[142:143] op_sel_hi:[1,0]
	v_pk_mul_f32 v[26:27], v[26:27], v[142:143] op_sel_hi:[1,0]
	v_pk_mul_f32 v[24:25], v[24:25], v[142:143] op_sel_hi:[1,0]
	v_pk_mul_f32 v[22:23], v[22:23], v[142:143] op_sel_hi:[1,0]
	v_pk_mul_f32 v[20:21], v[20:21], v[142:143] op_sel_hi:[1,0]
	v_pk_mul_f32 v[18:19], v[18:19], v[142:143] op_sel_hi:[1,0]
	v_pk_mul_f32 v[16:17], v[16:17], v[142:143] op_sel_hi:[1,0]
	v_pk_mul_f32 v[14:15], v[14:15], v[142:143] op_sel_hi:[1,0]
	v_pk_mul_f32 v[12:13], v[12:13], v[142:143] op_sel_hi:[1,0]
	v_pk_mul_f32 v[10:11], v[10:11], v[142:143] op_sel_hi:[1,0]
	v_pk_mul_f32 v[8:9], v[8:9], v[142:143] op_sel_hi:[1,0]
	v_pk_mul_f32 v[6:7], v[6:7], v[142:143] op_sel_hi:[1,0]
	v_pk_mul_f32 v[4:5], v[4:5], v[142:143] op_sel_hi:[1,0]
	v_pk_mul_f32 v[2:3], v[2:3], v[142:143] op_sel_hi:[1,0]
	v_pk_mul_f32 v[0:1], v[0:1], v[142:143] op_sel_hi:[1,0]
	s_branch .LBB0_964

; DI float rowmax32(const f32x16& s0, const f32x16& s1) {
;   float a = fmaxf(fmaxf(s0[0], s0[1]), s1[0]), b = fmaxf(fmaxf(s0[2], s0[3]), s1[1]); a = fmaxf(fmaxf(a, s1[2]), s1[3]);
; #pragma unroll
;   for (int r = 4; r < 16; r += 4) { a = fmaxf(fmaxf(a, s0[r]), s0[r + 1]); b = fmaxf(fmaxf(b, s0[r + 2]), s0[r + 3]); a = fmaxf(fmaxf(a, s1[r]), s1[r + 1]); b = fmaxf(fmaxf(b, s1[r + 2]), s1[r + 3]); }
;   const float m = fmaxf(a, b);
;   return fmaxf(m, __shfl_xor(m, 32));
; }
; template <int NDVB, bool HAS_NEXT> DI void softmax_def(f32x16& sa0, f32x16& sa1, f32x16& sb0, f32x16& sb1, f32x16 (&O)[NDVB], float& muse, float& l, bool first, bf16x8 (&P)[4], bool check = true) {
;   float mx = 0.f;
;   if (check) mx = rowmax32(sa0, sa1);
;   if (check && (first || __any(mx > 8.f))) {
;     float dl = first ? mx : fmaxf(mx, 0.f);
;     if (mx < -1e29f) dl = 0.f;
;     const float alpha = __builtin_amdgcn_exp2f(-dl);
;     muse += dl; l *= alpha;
; #pragma unroll
.LBB0_987:
	v_max_f32_e32 v129, v113, v113
	v_max_f32_e32 v130, v112, v112
	v_max_f32_e32 v129, v130, v129
	v_max3_f32 v130, v114, v115, v97
	v_max3_f32 v129, v129, v96, v98
	v_max3_f32 v129, v129, v99, v116
	v_max3_f32 v130, v130, v118, v119
	v_max3_f32 v129, v129, v117, v100
	v_max3_f32 v130, v130, v102, v103
	v_max3_f32 v129, v129, v101, v120
	v_max3_f32 v130, v130, v122, v123
	v_max3_f32 v129, v129, v121, v104
	v_max3_f32 v130, v130, v106, v107
	v_max3_f32 v129, v129, v105, v124
	v_max3_f32 v130, v130, v126, v127
	v_max3_f32 v129, v129, v125, v108
	v_max3_f32 v130, v130, v110, v111
	v_max3_f32 v129, v129, v109, v130
	v_mov_b32_e32 v130, v129
	s_cmp_lg_u32 s46, 3
	s_nop 1
	v_permlane32_swap_b32_e32 v130, v129
	v_max_f32_e32 v129, v129, v130
	s_cbranch_scc0 .LBB0_1005
	v_cmp_lt_f32_e32 vcc, s7, v129
	s_mov_b64 s[10:11], 0
	s_mov_b64 s[8:9], 0
	s_cbranch_vccz .LBB0_990
	v_max_f32_e32 v130, v129, v129
	v_max_f32_e32 v130, 0, v130
	s_mov_b64 s[8:9], -1

; DI float rowmax32(const f32x16& s0, const f32x16& s1) {
;   float a = fmaxf(fmaxf(s0[0], s0[1]), s1[0]), b = fmaxf(fmaxf(s0[2], s0[3]), s1[1]); a = fmaxf(fmaxf(a, s1[2]), s1[3]);
; #pragma unroll
;   for (int r = 4; r < 16; r += 4) { a = fmaxf(fmaxf(a, s0[r]), s0[r + 1]); b = fmaxf(fmaxf(b, s0[r + 2]), s0[r + 3]); a = fmaxf(fmaxf(a, s1[r]), s1[r + 1]); b = fmaxf(fmaxf(b, s1[r + 2]), s1[r + 3]); }
;   const float m = fmaxf(a, b);
;   return fmaxf(m, __shfl_xor(m, 32));
; }
; template <int NDVB, bool HAS_NEXT> DI void softmax_def(f32x16& sa0, f32x16& sa1, f32x16& sb0, f32x16& sb1, f32x16 (&O)[NDVB], float& muse, float& l, bool first, bf16x8 (&P)[4], bool check = true) {
;   float mx = 0.f;
;   if (check) mx = rowmax32(sa0, sa1);
;   if (check && (first || __any(mx > 8.f))) {
;     float dl = first ? mx : fmaxf(mx, 0.f);
;     if (mx < -1e29f) dl = 0.f;
;     const float alpha = __builtin_amdgcn_exp2f(-dl);
;     muse += dl; l *= alpha;
; #pragma unroll
;     for (int i = 0; i < 16; ++i) { sa0[i] -= dl; sa1[i] -= dl; }
;     if (HAS_NEXT) {
; #pragma unroll
;       for (int i = 0; i < 16; ++i) { sb0[i] -= dl; sb1[i] -= dl; }
;     }
; #pragma unroll
;     for (int d = 0; d < NDVB; ++d)
; #pragma unroll
;       for (int i = 0; i < 16; ++i) O[d][i] *= alpha;
;   }
.LBB0_1003:
	v_max_f32_e32 v96, v145, v145
	v_max_f32_e32 v97, v144, v144
	v_max_f32_e32 v96, v97, v96
	v_max3_f32 v97, v146, v147, v129
	v_max3_f32 v96, v96, v128, v130
	v_max3_f32 v96, v96, v131, v148
	v_max3_f32 v97, v97, v150, v151
	v_max3_f32 v96, v96, v149, v132
	v_max3_f32 v97, v97, v134, v135
	v_max3_f32 v96, v96, v133, v152
	v_max3_f32 v97, v97, v154, v155
	v_max3_f32 v96, v96, v153, v136
	v_max3_f32 v97, v97, v138, v139
	v_max3_f32 v96, v96, v137, v156
	v_max3_f32 v97, v97, v158, v159
	v_max3_f32 v96, v96, v157, v140
	v_max3_f32 v97, v97, v142, v143
	v_max3_f32 v96, v96, v141, v97
	v_mov_b32_e32 v97, v96
	s_nop 1
	v_permlane32_swap_b32_e32 v97, v96
	v_max_f32_e32 v96, v96, v97
	v_cmp_lt_f32_e32 vcc, s7, v96
	s_cbranch_vccz .LBB0_1006
	v_max_f32_e32 v97, v96, v96
	v_max_f32_e32 v97, 0, v97
	v_cmp_ngt_f32_e32 vcc, s85, v96
	s_nop 1
	v_cndmask_b32_e32 v96, 0, v97, vcc
	v_exp_f32_e64 v188, -v96
	v_add_f32_e32 v221, v221, v96
	v_pk_add_f32 v[144:145], v[144:145], v[96:97] op_sel_hi:[1,0] neg_lo:[0,1] neg_hi:[0,1]
	v_pk_add_f32 v[128:129], v[128:129], v[96:97] op_sel_hi:[1,0] neg_lo:[0,1] neg_hi:[0,1]
	v_mul_f32_e32 v223, v222, v188
	v_pk_add_f32 v[146:147], v[146:147], v[96:97] op_sel_hi:[1,0] neg_lo:[0,1] neg_hi:[0,1]
	v_pk_add_f32 v[130:131], v[130:131], v[96:97] op_sel_hi:[1,0] neg_lo:[0,1] neg_hi:[0,1]
	v_pk_add_f32 v[148:149], v[148:149], v[96:97] op_sel_hi:[1,0] neg_lo:[0,1] neg_hi:[0,1]
	v_pk_add_f32 v[132:133], v[132:133], v[96:97] op_sel_hi:[1,0] neg_lo:[0,1] neg_hi:[0,1]
	v_pk_add_f32 v[150:151], v[150:151], v[96:97] op_sel_hi:[1,0] neg_lo:[0,1] neg_hi:[0,1]
	v_pk_add_f32 v[134:135], v[134:135], v[96:97] op_sel_hi:[1,0] neg_lo:[0,1] neg_hi:[0,1]
	v_pk_add_f32 v[152:153], v[152:153], v[96:97] op_sel_hi:[1,0] neg_lo:[0,1] neg_hi:[0,1]
	v_pk_add_f32 v[136:137], v[136:137], v[96:97] op_sel_hi:[1,0] neg_lo:[0,1] neg_hi:[0,1]
	v_pk_add_f32 v[154:155], v[154:155], v[96:97] op_sel_hi:[1,0] neg_lo:[0,1] neg_hi:[0,1]
	v_pk_add_f32 v[138:139], v[138:139], v[96:97] op_sel_hi:[1,0] neg_lo:[0,1] neg_hi:[0,1]
	v_pk_add_f32 v[156:157], v[156:157], v[96:97] op_sel_hi:[1,0] neg_lo:[0,1] neg_hi:[0,1]
	v_pk_add_f32 v[140:141], v[140:141], v[96:97] op_sel_hi:[1,0] neg_lo:[0,1] neg_hi:[0,1]
	v_pk_add_f32 v[158:159], v[158:159], v[96:97] op_sel_hi:[1,0] neg_lo:[0,1] neg_hi:[0,1]
	v_pk_add_f32 v[142:143], v[142:143], v[96:97] op_sel_hi:[1,0] neg_lo:[0,1] neg_hi:[0,1]
	v_pk_mul_f32 v[62:63], v[62:63], v[188:189] op_sel_hi:[1,0]
	v_pk_mul_f32 v[60:61], v[60:61], v[188:189] op_sel_hi:[1,0]
	v_pk_mul_f32 v[58:59], v[58:59], v[188:189] op_sel_hi:[1,0]
	v_pk_mul_f32 v[56:57], v[56:57], v[188:189] op_sel_hi:[1,0]
	v_pk_mul_f32 v[54:55], v[54:55], v[188:189] op_sel_hi:[1,0]
	v_pk_mul_f32 v[52:53], v[52:53], v[188:189] op_sel_hi:[1,0]
	v_pk_mul_f32 v[50:51], v[50:51], v[188:189] op_sel_hi:[1,0]
	v_pk_mul_f32 v[48:49], v[48:49], v[188:189] op_sel_hi:[1,0]
	v_pk_mul_f32 v[46:47], v[46:47], v[188:189] op_sel_hi:[1,0]
	v_pk_mul_f32 v[44:45], v[44:45], v[188:189] op_sel_hi:[1,0]
	v_pk_mul_f32 v[42:43], v[42:43], v[188:189] op_sel_hi:[1,0]
	v_pk_mul_f32 v[40:41], v[40:41], v[188:189] op_sel_hi:[1,0]
	v_pk_mul_f32 v[38:39], v[38:39], v[188:189] op_sel_hi:[1,0]
	v_pk_mul_f32 v[36:37], v[36:37], v[188:189] op_sel_hi:[1,0]
	v_pk_mul_f32 v[34:35], v[34:35], v[188:189] op_sel_hi:[1,0]
	v_pk_mul_f32 v[32:33], v[32:33], v[188:189] op_sel_hi:[1,0]
	s_branch .LBB0_1007
